# cross-attention PV (key tiles 1..3): transposed V-fragment LDS reads run 3 MFMAs ahead in a ring of fresh buffers instead of read-wait(0)-MFMA per fragment
# speedup vs baseline: 1.0072x; 1.0072x over previous
; DI int tidx() { int t = threadIdx.x; asm volatile("" : "+v"(t)); return t; }
; DI void xattn_unit(const bf16_t* __restrict__ Qg, const bf16_t* __restrict__ Kg, const bf16_t* __restrict__ Vg, bf16_t* __restrict__ Og, lds_t* shm) {
;     ...
;   const int tid = tidx(), lane = tid & 63, h = lane >> 5, l31 = lane & 31, wid = __builtin_amdgcn_readfirstlane(tid >> 6);
;   unsigned soff[2];
; #pragma unroll
;   for (int i = 0; i < 2; ++i) { unsigned r, c; inv_off_a(tid + 512 * i, r, c); soff[i] = (r * (unsigned)LDKV + c * 8u) * 2u; }
;   constexpr unsigned tstep = 64u * LDKV * 2u;
;   auto issue_tile = [&](const bf16_t* src, int t, unsigned lds_base) __attribute__((always_inline)) {
;     const char* sb = (const char*)src + (size_t)t * tstep; lds_t* base = shm + lds_base + wid * 1024;
; #pragma unroll
;     for (int im = 0; im < 2; ++im) { glds16(sb + im * 256, soff[0], base + im * 16384); glds16(sb + im * 256, soff[1], base + im * 16384 + 8192); }
;   };
;   __syncthreads();
; #pragma unroll
;   for (int t = 0; t < 4; ++t) issue_tile(Kg, t, t * 32768);
;   issue_tile(Vg, 0, 131072);
;   const unsigned q4 = (lane & 15) >> 2, pp = lane & 3, blk = (lane >> 4) & 1;
;   const unsigned xk = (l31 >> 2) & 3, kbase = 2048u * (l31 >> 3) + 64u * (l31 & 7);
;   const unsigned ka0 = kbase + 16u * ((unsigned)h ^ xk), ka2 = kbase + 16u * ((2u + h) ^ xk);
;   const unsigned vrow = 64u * (4u * h + q4), cl = 2u * blk + (pp >> 1);
;   const unsigned va0 = vrow + 16u * (cl ^ (unsigned)h) + 8u * (pp & 1), va1 = vrow + 16u * (cl ^ ((unsigned)h ^ 2u)) + 8u * (pp & 1);
;   const unsigned qoff = ((unsigned)l31 * (unsigned)LDQ + 8u * h) * 2u;
;   f32x16 S[4][2];
; #pragma unroll
;   for (int t = 0; t < 4; ++t)
; #pragma unroll
;     for (int kb = 0; kb < 2; ++kb)
; #pragma unroll
;       for (int i = 0; i < 16; ++i) S[t][kb][i] = 0.f;
;   asm volatile("s_waitcnt vmcnt(0)" ::: "memory");
;   __syncthreads();
; DI void cross_attn_own_tiles(const Params& p, lds_t* shm) {
;     ...
;   for (int i = 0;; ++i) {
;     int pm, pn; if (!g8::tile_coords(i * (int)gridDim.x + (int)blockIdx.x, T_TOK / 256, 4, pm, pn)) break;
;     const int b = pm >> 5, hd = pn; const size_t r0 = (size_t)pm * 256 + wid * 32;
;     xattn_unit(Q + r0 * DM + hd * 256, KV + (size_t)b * 256 * 2048 + hd * 256, KV + (size_t)b * 256 * 2048 + 1024 + hd * 256, O + r0 * DM + hd * 256, shm);
.LBB0_629:
	s_add_i32 s0, s29, s0
	s_ashr_i32 s1, s0, 31
	s_lshr_b32 s1, s1, 27
	s_add_i32 s1, s0, s1
	s_ashr_i32 s28, s1, 5
	s_and_b32 s1, s1, 0xffe0
	s_sub_i32 s0, s0, s1
	s_bfe_i32 s1, s0, 0x80000
	s_bfe_u32 s1, s1, 0x3000c
	s_add_i32 s1, s0, s1
	s_bfe_i32 s29, s1, 0x80000
	s_and_b32 s1, s1, 0xf8
	s_sub_i32 s0, s0, s1
	s_lshl_b32 s28, s28, 3
	s_sext_i32_i8 s0, s0
	s_add_i32 s0, s28, s0
	s_ashr_i32 s1, s0, 31
	s_ashr_i32 s28, s0, 5
	s_lshl_b64 s[0:1], s[0:1], 18
	s_add_u32 s0, s0, s4
	s_addc_u32 s1, s1, s5
	s_lshl_b64 s[0:1], s[0:1], 1
	s_sext_i32_i16 s29, s29
	s_add_u32 s36, s26, s0
	s_addc_u32 s37, s27, s1
	s_lshl_b32 s29, s29, 5
	s_and_b32 s30, s29, 0xffffff00
	s_ashr_i32 s31, s30, 31
	s_lshl_b64 s[30:31], s[30:31], 1
	s_add_u32 s38, s36, s30
	s_addc_u32 s39, s37, s31
	s_ashr_i32 s29, s28, 31
	s_lshl_b64 s[28:29], s[28:29], 20
	s_add_u32 s28, s50, s28
	s_addc_u32 s29, s51, s29
	s_add_u32 s36, s28, s30
	s_addc_u32 s37, s29, s31
	s_add_u32 s0, s44, s0
	s_addc_u32 s1, s45, s1
	s_add_u32 s30, s0, s30
	v_mov_b32_e32 v6, v212
	s_addc_u32 s31, s1, s31
	s_mov_b32 s1, 0xfffff8
	v_bfe_u32 v1, v6, 2, 3
	v_lshrrev_b32_e32 v2, 4, v6
	v_and_or_b32 v2, v2, s1, v1
	v_lshrrev_b32_e32 v8, 3, v6
	v_lshrrev_b32_e32 v3, 2, v2
	v_and_b32_e32 v0, 12, v8
	v_xor_b32_e32 v3, v3, v6
	v_lshlrev_b32_e32 v7, 4, v6
	v_and_or_b32 v3, v3, 3, v0
	v_lshlrev_b32_e32 v2, 12, v2
	v_lshl_or_b32 v160, v3, 4, v2
	v_add_u32_e32 v2, 0x2000, v7
	v_readfirstlane_b32 s0, v6
	v_lshrrev_b32_e32 v2, 8, v2
	v_and_or_b32 v1, v2, s1, v1
	s_lshl_b32 s0, s0, 4
	v_lshrrev_b32_e32 v2, 2, v1
	s_and_b32 s82, s0, 0xfffffc00
	v_xor_b32_e32 v2, v2, v6
	s_add_i32 s78, s82, 0
	v_and_or_b32 v0, v2, 3, v0
	v_lshlrev_b32_e32 v1, 12, v1
	s_mov_b32 m0, s78
	v_lshl_or_b32 v162, v0, 4, v1
	s_barrier
	v_lshl_add_u64 v[0:1], s[36:37], 0, v[160:161]
	global_load_lds_dwordx4 v160, s[36:37]
	s_add_i32 m0, s78, 0x2000
	s_mov_b64 s[0:1], 0x100
	global_load_lds_dwordx4 v162, s[36:37]
	s_add_i32 m0, s78, 0x4000
	v_lshl_add_u64 v[4:5], v[0:1], 0, s[0:1]
	v_mov_b32_e32 v163, v161
	global_load_lds_dwordx4 v[4:5], off
	s_add_i32 m0, s78, 0x6000
	v_lshl_add_u64 v[2:3], s[36:37], 0, v[162:163]
	s_add_u32 s28, s36, 0x40000
	v_lshl_add_u64 v[4:5], v[2:3], 0, s[0:1]
	s_addc_u32 s29, s37, 0
	s_add_i32 s67, s78, 0x8000
	global_load_lds_dwordx4 v[4:5], off
	s_mov_b32 m0, s67
	s_add_i32 s0, s78, 0xa000
	global_load_lds_dwordx4 v160, s[28:29]
	s_mov_b32 m0, s0
	v_bfe_u32 v163, v6, 5, 1
	global_load_lds_dwordx4 v162, s[28:29]
	s_add_u32 s28, s36, 0x40100
	s_addc_u32 s29, s37, 0
	s_add_i32 s1, s78, 0xc000
	s_add_i32 vcc_lo, s78, 0xe000
	s_mov_b32 m0, s1
	s_add_u32 s68, s36, 0x80000
	global_load_lds_dwordx4 v160, s[28:29]
	s_mov_b32 m0, vcc_lo
	s_addc_u32 s69, s37, 0
	s_add_i32 vcc_hi, s78, 0x10000
	global_load_lds_dwordx4 v162, s[28:29]
	s_mov_b32 m0, vcc_hi
	s_add_i32 s28, s78, 0x12000
	global_load_lds_dwordx4 v160, s[68:69]
	s_mov_b32 m0, s28
	s_add_u32 s76, s36, 0x80100
	global_load_lds_dwordx4 v162, s[68:69]
	s_addc_u32 s77, s37, 0
	s_add_i32 s29, s78, 0x14000
	s_add_i32 s68, s78, 0x16000
	s_mov_b32 m0, s29
	s_add_u32 s80, s36, 0xc0000
	global_load_lds_dwordx4 v160, s[76:77]
	s_mov_b32 m0, s68
	s_addc_u32 s81, s37, 0
	s_add_i32 s69, s78, 0x18000
	global_load_lds_dwordx4 v162, s[76:77]
	s_mov_b32 m0, s69
	s_add_i32 s76, s78, 0x1a000
	global_load_lds_dwordx4 v160, s[80:81]
	s_mov_b32 m0, s76
	v_and_b32_e32 v132, 0xc0, v7
	global_load_lds_dwordx4 v162, s[80:81]
	s_add_u32 s80, s36, 0xc0100
	s_addc_u32 s81, s37, 0
	s_add_i32 s77, s78, 0x1c000
	s_mov_b32 m0, s77
	s_add_i32 s78, s78, 0x1e000
	global_load_lds_dwordx4 v160, s[80:81]
	s_mov_b32 m0, s78
	s_add_i32 s79, s14, s82
	global_load_lds_dwordx4 v162, s[80:81]
	s_mov_b64 s[80:81], 0x800
	v_lshl_add_u64 v[4:5], v[0:1], 0, s[80:81]
	s_mov_b32 m0, s79
	v_or_b32_e32 v7, 2, v163
	global_load_lds_dwordx4 v[4:5], off
	s_add_i32 m0, s79, 0x2000
	v_lshl_add_u64 v[4:5], v[2:3], 0, s[80:81]
	s_mov_b64 s[80:81], 0x900
	global_load_lds_dwordx4 v[4:5], off
	s_add_i32 m0, s79, 0x4000
	v_lshl_add_u64 v[0:1], v[0:1], 0, s[80:81]
	global_load_lds_dwordx4 v[0:1], off
	s_add_i32 m0, s79, 0x6000
	v_lshl_add_u64 v[0:1], v[2:3], 0, s[80:81]
	global_load_lds_dwordx4 v[0:1], off
	v_lshlrev_b32_e32 v1, 6, v6
	v_and_b32_e32 v5, 0x1c0, v1
	v_and_b32_e32 v1, 2, v8
	v_bfe_u32 v2, v6, 1, 1
	v_bitop3_b32 v3, v1, v163, v2 bitop3:0x36
	v_bitop3_b32 v1, v1, v7, v2 bitop3:0x36
	s_waitcnt vmcnt(0)
	v_lshlrev_b32_e32 v165, 4, v1
	v_lshlrev_b32_e32 v1, 11, v6
	v_lshlrev_b32_e32 v0, 8, v6
	v_and_b32_e32 v164, 0xf800, v1
	v_lshrrev_b32_e32 v4, 5, v6
	v_lshlrev_b32_e32 v169, 3, v6
	v_bfe_u32 v130, v6, 2, 2
	v_and_b32_e32 v6, 0x1800, v0
	v_lshlrev_b32_e32 v166, 4, v3
	v_lshl_or_b32 v128, v163, 4, v164
	s_waitcnt vmcnt(0) lgkmcnt(0)
	s_barrier
; #define LDSP(T, p) ((__attribute__((address_space(3))) T*)(p))
; #define MFMA32(a, b, c) __builtin_amdgcn_mfma_f32_32x32x16_bf16((a), (b), (c), 0, 0, 0)
; DI void xattn_unit(const bf16_t* __restrict__ Qg, const bf16_t* __restrict__ Kg, const bf16_t* __restrict__ Vg, bf16_t* __restrict__ Og, lds_t* shm) {
;     ...
; #pragma unroll
;   for (int ss = 0; ss < 16; ++ss) {
;     const int cgl = 2 * ss, img = cgl >> 4;
;     const bf16x8 qv = gld<bf16x8>(Qg + 16 * ss, qoff);
; #pragma unroll
;     for (int t = 0; t < 4; ++t)
; #pragma unroll
;       for (int kb = 0; kb < 2; ++kb) {
;         const bf16x8 kf = *LDSP(const bf16x8, shm + t * 32768 + img * 16384 + kb * 8192 + 512 * ((cgl & 15) >> 2) + ((cgl & 2) ? ka2 : ka0));
;         S[t][kb] = MFMA32(kf, qv, S[t][kb]);
;       }
;   }
	global_load_dwordx4 v[172:175], v128, s[38:39]
	global_load_dwordx4 v[176:179], v128, s[38:39] offset:32
	global_load_dwordx4 v[180:183], v128, s[38:39] offset:64
	global_load_dwordx4 v[184:187], v128, s[38:39] offset:96
	global_load_dwordx4 v[188:191], v128, s[38:39] offset:128
	global_load_dwordx4 v[192:195], v128, s[38:39] offset:160
	global_load_dwordx4 v[196:199], v128, s[38:39] offset:192
	global_load_dwordx4 v[200:203], v128, s[38:39] offset:224
	global_load_dwordx4 v[204:207], v128, s[38:39] offset:256
	global_load_dwordx4 v[208:211], v128, s[38:39] offset:288
	global_load_dwordx4 v[216:219], v128, s[38:39] offset:320
	global_load_dwordx4 v[220:223], v128, s[38:39] offset:352
	global_load_dwordx4 v[224:227], v128, s[38:39] offset:384
	global_load_dwordx4 v[228:231], v128, s[38:39] offset:416
	global_load_dwordx4 v[232:235], v128, s[38:39] offset:448
	global_load_dwordx4 v[236:239], v128, s[38:39] offset:480
	v_bitop3_b32 v4, v4, v130, 1 bitop3:0x6c
	v_add3_u32 v131, 0, v6, v5
	v_lshl_add_u32 v129, v4, 4, v131
	v_bitop3_b32 v130, v163, v130, 2 bitop3:0x36
	v_lshl_add_u32 v133, v130, 4, v131
	v_lshl_or_b32 v170, v163, 8, v132
	v_add_u32_e32 v248, 0x10000, v129
	v_add_u32_e32 v249, 0x10000, v133
	ds_read_b128 v[144:147], v129
	ds_read_b128 v[148:151], v129 offset:8192
	ds_read_b128 v[152:155], v129 offset:32768
	ds_read_b128 v[156:159], v129 offset:40960
	s_waitcnt vmcnt(15) lgkmcnt(3)
	v_mfma_f32_32x32x16_bf16 v[112:127], v[144:147], v[172:175], 0
	ds_read_b128 v[144:147], v248
	s_waitcnt lgkmcnt(3)
	v_mfma_f32_32x32x16_bf16 v[96:111], v[148:151], v[172:175], 0
	ds_read_b128 v[148:151], v248 offset:8192
	s_waitcnt lgkmcnt(3)
	v_mfma_f32_32x32x16_bf16 v[80:95], v[152:155], v[172:175], 0
	ds_read_b128 v[152:155], v248 offset:32768
	s_waitcnt lgkmcnt(3)
	v_mfma_f32_32x32x16_bf16 v[64:79], v[156:159], v[172:175], 0
	ds_read_b128 v[156:159], v248 offset:40960
	s_waitcnt lgkmcnt(3)
	v_mfma_f32_32x32x16_bf16 v[48:63], v[144:147], v[172:175], 0
	ds_read_b128 v[144:147], v133
	s_waitcnt lgkmcnt(3)
	v_mfma_f32_32x32x16_bf16 v[32:47], v[148:151], v[172:175], 0
	ds_read_b128 v[148:151], v133 offset:8192
	s_waitcnt lgkmcnt(3)
	v_mfma_f32_32x32x16_bf16 v[16:31], v[152:155], v[172:175], 0
	ds_read_b128 v[152:155], v133 offset:32768
	s_waitcnt lgkmcnt(3)
	v_mfma_f32_32x32x16_bf16 v[0:15], v[156:159], v[172:175], 0
	ds_read_b128 v[156:159], v133 offset:40960
	s_waitcnt vmcnt(14) lgkmcnt(3)
	v_mfma_f32_32x32x16_bf16 v[112:127], v[144:147], v[176:179], v[112:127]
	ds_read_b128 v[144:147], v249
	s_waitcnt lgkmcnt(3)
	v_mfma_f32_32x32x16_bf16 v[96:111], v[148:151], v[176:179], v[96:111]
	ds_read_b128 v[148:151], v249 offset:8192
	s_waitcnt lgkmcnt(3)
	v_mfma_f32_32x32x16_bf16 v[80:95], v[152:155], v[176:179], v[80:95]
	ds_read_b128 v[152:155], v249 offset:32768
	s_waitcnt lgkmcnt(3)
	v_mfma_f32_32x32x16_bf16 v[64:79], v[156:159], v[176:179], v[64:79]
	ds_read_b128 v[156:159], v249 offset:40960
	s_waitcnt lgkmcnt(3)
	v_mfma_f32_32x32x16_bf16 v[48:63], v[144:147], v[176:179], v[48:63]
	ds_read_b128 v[144:147], v129 offset:512
	s_waitcnt lgkmcnt(3)
	v_mfma_f32_32x32x16_bf16 v[32:47], v[148:151], v[176:179], v[32:47]
	ds_read_b128 v[148:151], v129 offset:8704
	s_waitcnt lgkmcnt(3)
	v_mfma_f32_32x32x16_bf16 v[16:31], v[152:155], v[176:179], v[16:31]
	ds_read_b128 v[152:155], v129 offset:33280
	s_waitcnt lgkmcnt(3)
	v_mfma_f32_32x32x16_bf16 v[0:15], v[156:159], v[176:179], v[0:15]
	ds_read_b128 v[156:159], v129 offset:41472
	s_waitcnt vmcnt(13) lgkmcnt(3)
	v_mfma_f32_32x32x16_bf16 v[112:127], v[144:147], v[180:183], v[112:127]
	ds_read_b128 v[144:147], v248 offset:512
	s_waitcnt lgkmcnt(3)
	v_mfma_f32_32x32x16_bf16 v[96:111], v[148:151], v[180:183], v[96:111]
	ds_read_b128 v[148:151], v248 offset:8704
	s_waitcnt lgkmcnt(3)
	v_mfma_f32_32x32x16_bf16 v[80:95], v[152:155], v[180:183], v[80:95]
	ds_read_b128 v[152:155], v248 offset:33280
	s_waitcnt lgkmcnt(3)
	v_mfma_f32_32x32x16_bf16 v[64:79], v[156:159], v[180:183], v[64:79]
	ds_read_b128 v[156:159], v248 offset:41472
	s_waitcnt lgkmcnt(3)
	v_mfma_f32_32x32x16_bf16 v[48:63], v[144:147], v[180:183], v[48:63]
	ds_read_b128 v[144:147], v133 offset:512
	s_waitcnt lgkmcnt(3)
	v_mfma_f32_32x32x16_bf16 v[32:47], v[148:151], v[180:183], v[32:47]
	ds_read_b128 v[148:151], v133 offset:8704
	s_waitcnt lgkmcnt(3)
	v_mfma_f32_32x32x16_bf16 v[16:31], v[152:155], v[180:183], v[16:31]
	ds_read_b128 v[152:155], v133 offset:33280
	s_waitcnt lgkmcnt(3)
	v_mfma_f32_32x32x16_bf16 v[0:15], v[156:159], v[180:183], v[0:15]
	ds_read_b128 v[156:159], v133 offset:41472
	s_waitcnt vmcnt(12) lgkmcnt(3)
	v_mfma_f32_32x32x16_bf16 v[112:127], v[144:147], v[184:187], v[112:127]
	ds_read_b128 v[144:147], v249 offset:512
	s_waitcnt lgkmcnt(3)
	v_mfma_f32_32x32x16_bf16 v[96:111], v[148:151], v[184:187], v[96:111]
	ds_read_b128 v[148:151], v249 offset:8704
	s_waitcnt lgkmcnt(3)
	v_mfma_f32_32x32x16_bf16 v[80:95], v[152:155], v[184:187], v[80:95]
	ds_read_b128 v[152:155], v249 offset:33280
	s_waitcnt lgkmcnt(3)
	v_mfma_f32_32x32x16_bf16 v[64:79], v[156:159], v[184:187], v[64:79]
	ds_read_b128 v[156:159], v249 offset:41472
	s_waitcnt lgkmcnt(3)
	v_mfma_f32_32x32x16_bf16 v[48:63], v[144:147], v[184:187], v[48:63]
	ds_read_b128 v[144:147], v129 offset:1024
	s_waitcnt lgkmcnt(3)
	v_mfma_f32_32x32x16_bf16 v[32:47], v[148:151], v[184:187], v[32:47]
	ds_read_b128 v[148:151], v129 offset:9216
	s_waitcnt lgkmcnt(3)
	v_mfma_f32_32x32x16_bf16 v[16:31], v[152:155], v[184:187], v[16:31]
	ds_read_b128 v[152:155], v129 offset:33792
	s_waitcnt lgkmcnt(3)
	v_mfma_f32_32x32x16_bf16 v[0:15], v[156:159], v[184:187], v[0:15]
	ds_read_b128 v[156:159], v129 offset:41984
	s_waitcnt vmcnt(11) lgkmcnt(3)
; #define LDSP(T, p) ((__attribute__((address_space(3))) T*)(p))
; #define MFMA32(a, b, c) __builtin_amdgcn_mfma_f32_32x32x16_bf16((a), (b), (c), 0, 0, 0)
; DI void xattn_unit(const bf16_t* __restrict__ Qg, const bf16_t* __restrict__ Kg, const bf16_t* __restrict__ Vg, bf16_t* __restrict__ Og, lds_t* shm) {
;     ...
; #pragma unroll
;   for (int ss = 0; ss < 16; ++ss) {
;     const int cgl = 2 * ss, img = cgl >> 4;
;     const bf16x8 qv = gld<bf16x8>(Qg + 16 * ss, qoff);
; #pragma unroll
;     for (int t = 0; t < 4; ++t)
; #pragma unroll
;       for (int kb = 0; kb < 2; ++kb) {
;         const bf16x8 kf = *LDSP(const bf16x8, shm + t * 32768 + img * 16384 + kb * 8192 + 512 * ((cgl & 15) >> 2) + ((cgl & 2) ? ka2 : ka0));
;         S[t][kb] = MFMA32(kf, qv, S[t][kb]);
;       }
;   }
	v_mfma_f32_32x32x16_bf16 v[112:127], v[144:147], v[188:191], v[112:127]
	ds_read_b128 v[144:147], v248 offset:1024
	s_waitcnt lgkmcnt(3)
	v_mfma_f32_32x32x16_bf16 v[96:111], v[148:151], v[188:191], v[96:111]
	ds_read_b128 v[148:151], v248 offset:9216
	s_waitcnt lgkmcnt(3)
	v_mfma_f32_32x32x16_bf16 v[80:95], v[152:155], v[188:191], v[80:95]
	ds_read_b128 v[152:155], v248 offset:33792
	s_waitcnt lgkmcnt(3)
	v_mfma_f32_32x32x16_bf16 v[64:79], v[156:159], v[188:191], v[64:79]
	ds_read_b128 v[156:159], v248 offset:41984
	s_waitcnt lgkmcnt(3)
	v_mfma_f32_32x32x16_bf16 v[48:63], v[144:147], v[188:191], v[48:63]
	ds_read_b128 v[144:147], v133 offset:1024
	s_waitcnt lgkmcnt(3)
	v_mfma_f32_32x32x16_bf16 v[32:47], v[148:151], v[188:191], v[32:47]
	ds_read_b128 v[148:151], v133 offset:9216
	s_waitcnt lgkmcnt(3)
	v_mfma_f32_32x32x16_bf16 v[16:31], v[152:155], v[188:191], v[16:31]
	ds_read_b128 v[152:155], v133 offset:33792
	s_waitcnt lgkmcnt(3)
	v_mfma_f32_32x32x16_bf16 v[0:15], v[156:159], v[188:191], v[0:15]
	ds_read_b128 v[156:159], v133 offset:41984
	s_waitcnt vmcnt(10) lgkmcnt(3)
	v_mfma_f32_32x32x16_bf16 v[112:127], v[144:147], v[192:195], v[112:127]
	ds_read_b128 v[144:147], v249 offset:1024
	s_waitcnt lgkmcnt(3)
	v_mfma_f32_32x32x16_bf16 v[96:111], v[148:151], v[192:195], v[96:111]
	ds_read_b128 v[148:151], v249 offset:9216
	s_waitcnt lgkmcnt(3)
	v_mfma_f32_32x32x16_bf16 v[80:95], v[152:155], v[192:195], v[80:95]
	ds_read_b128 v[152:155], v249 offset:33792
	s_waitcnt lgkmcnt(3)
	v_mfma_f32_32x32x16_bf16 v[64:79], v[156:159], v[192:195], v[64:79]
	ds_read_b128 v[156:159], v249 offset:41984
	s_waitcnt lgkmcnt(3)
	v_mfma_f32_32x32x16_bf16 v[48:63], v[144:147], v[192:195], v[48:63]
	ds_read_b128 v[144:147], v129 offset:1536
	s_waitcnt lgkmcnt(3)
	v_mfma_f32_32x32x16_bf16 v[32:47], v[148:151], v[192:195], v[32:47]
	ds_read_b128 v[148:151], v129 offset:9728
	s_waitcnt lgkmcnt(3)
	v_mfma_f32_32x32x16_bf16 v[16:31], v[152:155], v[192:195], v[16:31]
	ds_read_b128 v[152:155], v129 offset:34304
	s_waitcnt lgkmcnt(3)
	v_mfma_f32_32x32x16_bf16 v[0:15], v[156:159], v[192:195], v[0:15]
	ds_read_b128 v[156:159], v129 offset:42496
	s_waitcnt vmcnt(9) lgkmcnt(3)
	v_mfma_f32_32x32x16_bf16 v[112:127], v[144:147], v[196:199], v[112:127]
	ds_read_b128 v[144:147], v248 offset:1536
	s_waitcnt lgkmcnt(3)
	v_mfma_f32_32x32x16_bf16 v[96:111], v[148:151], v[196:199], v[96:111]
	ds_read_b128 v[148:151], v248 offset:9728
	s_waitcnt lgkmcnt(3)
	v_mfma_f32_32x32x16_bf16 v[80:95], v[152:155], v[196:199], v[80:95]
	ds_read_b128 v[152:155], v248 offset:34304
	s_waitcnt lgkmcnt(3)
	v_mfma_f32_32x32x16_bf16 v[64:79], v[156:159], v[196:199], v[64:79]
	ds_read_b128 v[156:159], v248 offset:42496
	s_waitcnt lgkmcnt(3)
	v_mfma_f32_32x32x16_bf16 v[48:63], v[144:147], v[196:199], v[48:63]
	ds_read_b128 v[144:147], v133 offset:1536
	s_waitcnt lgkmcnt(3)
	v_mfma_f32_32x32x16_bf16 v[32:47], v[148:151], v[196:199], v[32:47]
	ds_read_b128 v[148:151], v133 offset:9728
	s_waitcnt lgkmcnt(3)
	v_mfma_f32_32x32x16_bf16 v[16:31], v[152:155], v[196:199], v[16:31]
	ds_read_b128 v[152:155], v133 offset:34304
	s_waitcnt lgkmcnt(3)
	v_mfma_f32_32x32x16_bf16 v[0:15], v[156:159], v[196:199], v[0:15]
	ds_read_b128 v[156:159], v133 offset:42496
	s_waitcnt vmcnt(8) lgkmcnt(3)
	v_mfma_f32_32x32x16_bf16 v[112:127], v[144:147], v[200:203], v[112:127]
	ds_read_b128 v[144:147], v249 offset:1536
	s_waitcnt lgkmcnt(3)
	v_mfma_f32_32x32x16_bf16 v[96:111], v[148:151], v[200:203], v[96:111]
	ds_read_b128 v[148:151], v249 offset:9728
	s_waitcnt lgkmcnt(3)
	v_mfma_f32_32x32x16_bf16 v[80:95], v[152:155], v[200:203], v[80:95]
	ds_read_b128 v[152:155], v249 offset:34304
	s_waitcnt lgkmcnt(3)
	v_mfma_f32_32x32x16_bf16 v[64:79], v[156:159], v[200:203], v[64:79]
	ds_read_b128 v[156:159], v249 offset:42496
	s_waitcnt lgkmcnt(3)
	v_mfma_f32_32x32x16_bf16 v[48:63], v[144:147], v[200:203], v[48:63]
	ds_read_b128 v[144:147], v129 offset:16384
	s_waitcnt lgkmcnt(3)
	v_mfma_f32_32x32x16_bf16 v[32:47], v[148:151], v[200:203], v[32:47]
	ds_read_b128 v[148:151], v129 offset:24576
	s_waitcnt lgkmcnt(3)
	v_mfma_f32_32x32x16_bf16 v[16:31], v[152:155], v[200:203], v[16:31]
	ds_read_b128 v[152:155], v129 offset:49152
	s_waitcnt lgkmcnt(3)
	v_mfma_f32_32x32x16_bf16 v[0:15], v[156:159], v[200:203], v[0:15]
	ds_read_b128 v[156:159], v129 offset:57344
	s_waitcnt vmcnt(7) lgkmcnt(3)
	v_mfma_f32_32x32x16_bf16 v[112:127], v[144:147], v[204:207], v[112:127]
	ds_read_b128 v[144:147], v248 offset:16384
	s_waitcnt lgkmcnt(3)
	v_mfma_f32_32x32x16_bf16 v[96:111], v[148:151], v[204:207], v[96:111]
	ds_read_b128 v[148:151], v248 offset:24576
	s_waitcnt lgkmcnt(3)
	v_mfma_f32_32x32x16_bf16 v[80:95], v[152:155], v[204:207], v[80:95]
	ds_read_b128 v[152:155], v248 offset:49152
	s_waitcnt lgkmcnt(3)
	v_mfma_f32_32x32x16_bf16 v[64:79], v[156:159], v[204:207], v[64:79]
	ds_read_b128 v[156:159], v248 offset:57344
	s_waitcnt lgkmcnt(3)
	v_mfma_f32_32x32x16_bf16 v[48:63], v[144:147], v[204:207], v[48:63]
	ds_read_b128 v[144:147], v133 offset:16384
	s_waitcnt lgkmcnt(3)
	v_mfma_f32_32x32x16_bf16 v[32:47], v[148:151], v[204:207], v[32:47]
	ds_read_b128 v[148:151], v133 offset:24576
	s_waitcnt lgkmcnt(3)
	v_mfma_f32_32x32x16_bf16 v[16:31], v[152:155], v[204:207], v[16:31]
	ds_read_b128 v[152:155], v133 offset:49152
	s_waitcnt lgkmcnt(3)
	v_mfma_f32_32x32x16_bf16 v[0:15], v[156:159], v[204:207], v[0:15]
	ds_read_b128 v[156:159], v133 offset:57344
	s_waitcnt vmcnt(6) lgkmcnt(3)
	v_mfma_f32_32x32x16_bf16 v[112:127], v[144:147], v[208:211], v[112:127]
	ds_read_b128 v[144:147], v249 offset:16384
	s_waitcnt lgkmcnt(3)
; #define LDSP(T, p) ((__attribute__((address_space(3))) T*)(p))
; #define MFMA32(a, b, c) __builtin_amdgcn_mfma_f32_32x32x16_bf16((a), (b), (c), 0, 0, 0)
; DI void xattn_unit(const bf16_t* __restrict__ Qg, const bf16_t* __restrict__ Kg, const bf16_t* __restrict__ Vg, bf16_t* __restrict__ Og, lds_t* shm) {
;     ...
; #pragma unroll
;   for (int ss = 0; ss < 16; ++ss) {
;     const int cgl = 2 * ss, img = cgl >> 4;
;     const bf16x8 qv = gld<bf16x8>(Qg + 16 * ss, qoff);
; #pragma unroll
;     for (int t = 0; t < 4; ++t)
; #pragma unroll
;       for (int kb = 0; kb < 2; ++kb) {
;         const bf16x8 kf = *LDSP(const bf16x8, shm + t * 32768 + img * 16384 + kb * 8192 + 512 * ((cgl & 15) >> 2) + ((cgl & 2) ? ka2 : ka0));
;         S[t][kb] = MFMA32(kf, qv, S[t][kb]);
;       }
;   }
	v_mfma_f32_32x32x16_bf16 v[96:111], v[148:151], v[208:211], v[96:111]
	ds_read_b128 v[148:151], v249 offset:24576
	s_waitcnt lgkmcnt(3)
	v_mfma_f32_32x32x16_bf16 v[80:95], v[152:155], v[208:211], v[80:95]
	ds_read_b128 v[152:155], v249 offset:49152
	s_waitcnt lgkmcnt(3)
	v_mfma_f32_32x32x16_bf16 v[64:79], v[156:159], v[208:211], v[64:79]
	ds_read_b128 v[156:159], v249 offset:57344
	s_waitcnt lgkmcnt(3)
	v_mfma_f32_32x32x16_bf16 v[48:63], v[144:147], v[208:211], v[48:63]
	ds_read_b128 v[144:147], v129 offset:16896
	s_waitcnt lgkmcnt(3)
	v_mfma_f32_32x32x16_bf16 v[32:47], v[148:151], v[208:211], v[32:47]
	ds_read_b128 v[148:151], v129 offset:25088
	s_waitcnt lgkmcnt(3)
	v_mfma_f32_32x32x16_bf16 v[16:31], v[152:155], v[208:211], v[16:31]
	ds_read_b128 v[152:155], v129 offset:49664
	s_waitcnt lgkmcnt(3)
	v_mfma_f32_32x32x16_bf16 v[0:15], v[156:159], v[208:211], v[0:15]
	ds_read_b128 v[156:159], v129 offset:57856
	s_waitcnt vmcnt(5) lgkmcnt(3)
	v_mfma_f32_32x32x16_bf16 v[112:127], v[144:147], v[216:219], v[112:127]
	ds_read_b128 v[144:147], v248 offset:16896
	s_waitcnt lgkmcnt(3)
	v_mfma_f32_32x32x16_bf16 v[96:111], v[148:151], v[216:219], v[96:111]
	ds_read_b128 v[148:151], v248 offset:25088
	s_waitcnt lgkmcnt(3)
	v_mfma_f32_32x32x16_bf16 v[80:95], v[152:155], v[216:219], v[80:95]
	ds_read_b128 v[152:155], v248 offset:49664
	s_waitcnt lgkmcnt(3)
	v_mfma_f32_32x32x16_bf16 v[64:79], v[156:159], v[216:219], v[64:79]
	ds_read_b128 v[156:159], v248 offset:57856
	s_waitcnt lgkmcnt(3)
	v_mfma_f32_32x32x16_bf16 v[48:63], v[144:147], v[216:219], v[48:63]
	ds_read_b128 v[144:147], v133 offset:16896
	s_waitcnt lgkmcnt(3)
	v_mfma_f32_32x32x16_bf16 v[32:47], v[148:151], v[216:219], v[32:47]
	ds_read_b128 v[148:151], v133 offset:25088
	s_waitcnt lgkmcnt(3)
	v_mfma_f32_32x32x16_bf16 v[16:31], v[152:155], v[216:219], v[16:31]
	ds_read_b128 v[152:155], v133 offset:49664
	s_waitcnt lgkmcnt(3)
	v_mfma_f32_32x32x16_bf16 v[0:15], v[156:159], v[216:219], v[0:15]
	ds_read_b128 v[156:159], v133 offset:57856
	s_waitcnt vmcnt(4) lgkmcnt(3)
	v_mfma_f32_32x32x16_bf16 v[112:127], v[144:147], v[220:223], v[112:127]
	ds_read_b128 v[144:147], v249 offset:16896
	s_waitcnt lgkmcnt(3)
	v_mfma_f32_32x32x16_bf16 v[96:111], v[148:151], v[220:223], v[96:111]
	ds_read_b128 v[148:151], v249 offset:25088
	s_waitcnt lgkmcnt(3)
	v_mfma_f32_32x32x16_bf16 v[80:95], v[152:155], v[220:223], v[80:95]
	ds_read_b128 v[152:155], v249 offset:49664
	s_waitcnt lgkmcnt(3)
	v_mfma_f32_32x32x16_bf16 v[64:79], v[156:159], v[220:223], v[64:79]
	ds_read_b128 v[156:159], v249 offset:57856
	s_waitcnt lgkmcnt(3)
	v_mfma_f32_32x32x16_bf16 v[48:63], v[144:147], v[220:223], v[48:63]
	ds_read_b128 v[144:147], v129 offset:17408
	s_waitcnt lgkmcnt(3)
	v_mfma_f32_32x32x16_bf16 v[32:47], v[148:151], v[220:223], v[32:47]
	ds_read_b128 v[148:151], v129 offset:25600
	s_waitcnt lgkmcnt(3)
	v_mfma_f32_32x32x16_bf16 v[16:31], v[152:155], v[220:223], v[16:31]
	ds_read_b128 v[152:155], v129 offset:50176
	s_waitcnt lgkmcnt(3)
	v_mfma_f32_32x32x16_bf16 v[0:15], v[156:159], v[220:223], v[0:15]
	ds_read_b128 v[156:159], v129 offset:58368
	s_waitcnt vmcnt(3) lgkmcnt(3)
	v_mfma_f32_32x32x16_bf16 v[112:127], v[144:147], v[224:227], v[112:127]
	ds_read_b128 v[144:147], v248 offset:17408
	s_waitcnt lgkmcnt(3)
	v_mfma_f32_32x32x16_bf16 v[96:111], v[148:151], v[224:227], v[96:111]
	ds_read_b128 v[148:151], v248 offset:25600
	s_waitcnt lgkmcnt(3)
	v_mfma_f32_32x32x16_bf16 v[80:95], v[152:155], v[224:227], v[80:95]
	ds_read_b128 v[152:155], v248 offset:50176
	s_waitcnt lgkmcnt(3)
	v_mfma_f32_32x32x16_bf16 v[64:79], v[156:159], v[224:227], v[64:79]
	ds_read_b128 v[156:159], v248 offset:58368
	s_waitcnt lgkmcnt(3)
	v_mfma_f32_32x32x16_bf16 v[48:63], v[144:147], v[224:227], v[48:63]
	ds_read_b128 v[144:147], v133 offset:17408
	s_waitcnt lgkmcnt(3)
	v_mfma_f32_32x32x16_bf16 v[32:47], v[148:151], v[224:227], v[32:47]
	ds_read_b128 v[148:151], v133 offset:25600
	s_waitcnt lgkmcnt(3)
	v_mfma_f32_32x32x16_bf16 v[16:31], v[152:155], v[224:227], v[16:31]
	ds_read_b128 v[152:155], v133 offset:50176
	s_waitcnt lgkmcnt(3)
	v_mfma_f32_32x32x16_bf16 v[0:15], v[156:159], v[224:227], v[0:15]
	ds_read_b128 v[156:159], v133 offset:58368
	s_waitcnt vmcnt(2) lgkmcnt(3)
	v_mfma_f32_32x32x16_bf16 v[112:127], v[144:147], v[228:231], v[112:127]
	ds_read_b128 v[144:147], v249 offset:17408
	s_waitcnt lgkmcnt(3)
	v_mfma_f32_32x32x16_bf16 v[96:111], v[148:151], v[228:231], v[96:111]
	ds_read_b128 v[148:151], v249 offset:25600
	s_waitcnt lgkmcnt(3)
	v_mfma_f32_32x32x16_bf16 v[80:95], v[152:155], v[228:231], v[80:95]
	ds_read_b128 v[152:155], v249 offset:50176
	s_waitcnt lgkmcnt(3)
	v_mfma_f32_32x32x16_bf16 v[64:79], v[156:159], v[228:231], v[64:79]
	ds_read_b128 v[156:159], v249 offset:58368
	s_waitcnt lgkmcnt(3)
	v_mfma_f32_32x32x16_bf16 v[48:63], v[144:147], v[228:231], v[48:63]
	ds_read_b128 v[144:147], v129 offset:17920
	s_waitcnt lgkmcnt(3)
	v_mfma_f32_32x32x16_bf16 v[32:47], v[148:151], v[228:231], v[32:47]
	ds_read_b128 v[148:151], v129 offset:26112
	s_waitcnt lgkmcnt(3)
	v_mfma_f32_32x32x16_bf16 v[16:31], v[152:155], v[228:231], v[16:31]
	ds_read_b128 v[152:155], v129 offset:50688
	s_waitcnt lgkmcnt(3)
	v_mfma_f32_32x32x16_bf16 v[0:15], v[156:159], v[228:231], v[0:15]
	ds_read_b128 v[156:159], v129 offset:58880
	s_waitcnt vmcnt(1) lgkmcnt(3)
	v_mfma_f32_32x32x16_bf16 v[112:127], v[144:147], v[232:235], v[112:127]
	ds_read_b128 v[144:147], v248 offset:17920
	s_waitcnt lgkmcnt(3)
	v_mfma_f32_32x32x16_bf16 v[96:111], v[148:151], v[232:235], v[96:111]
	ds_read_b128 v[148:151], v248 offset:26112
	s_waitcnt lgkmcnt(3)
; DI void xattn_unit(const bf16_t* __restrict__ Qg, const bf16_t* __restrict__ Kg, const bf16_t* __restrict__ Vg, bf16_t* __restrict__ Og, lds_t* shm) {
;     ...
;   float mx = S[0][0][0];
; #pragma unroll
;   for (int t = 0; t < 4; ++t)
; #pragma unroll
;     for (int kb = 0; kb < 2; ++kb)
; #pragma unroll
;       for (int i = 0; i < 16; ++i) mx = fmaxf(mx, S[t][kb][i]);
;   { const auto sw = __builtin_amdgcn_permlane32_swap(__float_as_uint(mx), __float_as_uint(mx), false, false); mx = fmaxf(__uint_as_float(sw[0]), __uint_as_float(sw[1])); }
;   float rs = 0.f;
;   bf16x8 P[4][2][2];
; #pragma unroll
;   for (int t = 0; t < 4; ++t)
; #pragma unroll
;     for (int kb = 0; kb < 2; ++kb)
; #pragma unroll
;       for (int s2 = 0; s2 < 2; ++s2) {
;         float e[8];
; #pragma unroll
;         for (int j = 0; j < 8; ++j) { e[j] = __builtin_amdgcn_exp2f(S[t][kb][8 * s2 + j] - mx); rs += e[j]; }
	v_mfma_f32_32x32x16_bf16 v[80:95], v[152:155], v[232:235], v[80:95]
	ds_read_b128 v[152:155], v248 offset:50688
	s_waitcnt lgkmcnt(3)
	v_mfma_f32_32x32x16_bf16 v[64:79], v[156:159], v[232:235], v[64:79]
	ds_read_b128 v[156:159], v248 offset:58880
	s_waitcnt lgkmcnt(3)
	v_mfma_f32_32x32x16_bf16 v[48:63], v[144:147], v[232:235], v[48:63]
	ds_read_b128 v[144:147], v133 offset:17920
	s_waitcnt lgkmcnt(3)
	v_mfma_f32_32x32x16_bf16 v[32:47], v[148:151], v[232:235], v[32:47]
	ds_read_b128 v[148:151], v133 offset:26112
	s_waitcnt lgkmcnt(3)
	v_mfma_f32_32x32x16_bf16 v[16:31], v[152:155], v[232:235], v[16:31]
	ds_read_b128 v[152:155], v133 offset:50688
	s_waitcnt lgkmcnt(3)
	v_mfma_f32_32x32x16_bf16 v[0:15], v[156:159], v[232:235], v[0:15]
	ds_read_b128 v[156:159], v133 offset:58880
	s_waitcnt vmcnt(0) lgkmcnt(3)
	v_mfma_f32_32x32x16_bf16 v[112:127], v[144:147], v[236:239], v[112:127]
	ds_read_b128 v[144:147], v249 offset:17920
	s_waitcnt lgkmcnt(3)
	v_mfma_f32_32x32x16_bf16 v[96:111], v[148:151], v[236:239], v[96:111]
	ds_read_b128 v[148:151], v249 offset:26112
	s_waitcnt lgkmcnt(3)
	v_mfma_f32_32x32x16_bf16 v[80:95], v[152:155], v[236:239], v[80:95]
	ds_read_b128 v[152:155], v249 offset:50688
	s_waitcnt lgkmcnt(3)
	v_mfma_f32_32x32x16_bf16 v[64:79], v[156:159], v[236:239], v[64:79]
	ds_read_b128 v[156:159], v249 offset:58880
	s_waitcnt lgkmcnt(3)
	v_mfma_f32_32x32x16_bf16 v[48:63], v[144:147], v[236:239], v[48:63]
	s_waitcnt lgkmcnt(2)
	v_mfma_f32_32x32x16_bf16 v[32:47], v[148:151], v[236:239], v[32:47]
	s_waitcnt lgkmcnt(1)
	v_mfma_f32_32x32x16_bf16 v[16:31], v[152:155], v[236:239], v[16:31]
	s_waitcnt lgkmcnt(0)
	v_mfma_f32_32x32x16_bf16 v[0:15], v[156:159], v[236:239], v[0:15]
	v_max_f32_e32 v128, v113, v113
	v_max_f32_e32 v129, v112, v112
	v_max_f32_e32 v128, v129, v128
	v_max3_f32 v128, v128, v114, v115
	v_max3_f32 v128, v128, v116, v117
	v_max3_f32 v128, v128, v118, v119
	v_max3_f32 v128, v128, v120, v121
	v_max3_f32 v128, v128, v122, v123
	v_max3_f32 v128, v128, v124, v125
	v_max3_f32 v128, v128, v126, v127
	v_max3_f32 v128, v128, v96, v97
	v_max3_f32 v128, v128, v98, v99
	v_max3_f32 v128, v128, v100, v101
	v_max3_f32 v128, v128, v102, v103
	v_max3_f32 v128, v128, v104, v105
	v_max3_f32 v128, v128, v106, v107
	v_max3_f32 v128, v128, v108, v109
	v_max3_f32 v128, v128, v110, v111
	v_max3_f32 v128, v128, v80, v81
	v_max3_f32 v128, v128, v82, v83
	v_max3_f32 v128, v128, v84, v85
	v_max3_f32 v128, v128, v86, v87
	v_max3_f32 v128, v128, v88, v89
	v_max3_f32 v128, v128, v90, v91
	v_max3_f32 v128, v128, v92, v93
	v_max3_f32 v128, v128, v94, v95
	v_max3_f32 v128, v128, v64, v65
	v_max3_f32 v128, v128, v66, v67
	v_max3_f32 v128, v128, v68, v69
	v_max3_f32 v128, v128, v70, v71
	v_max3_f32 v128, v128, v72, v73
	v_max3_f32 v128, v128, v74, v75
	v_max3_f32 v128, v128, v76, v77
	v_max3_f32 v128, v128, v78, v79
	v_max3_f32 v128, v128, v48, v49
	v_max3_f32 v128, v128, v50, v51
	v_max3_f32 v128, v128, v52, v53
	v_max3_f32 v128, v128, v54, v55
	v_max3_f32 v128, v128, v56, v57
	v_max3_f32 v128, v128, v58, v59
	v_max3_f32 v128, v128, v60, v61
	v_max3_f32 v128, v128, v62, v63
	v_max3_f32 v128, v128, v32, v33
	v_max3_f32 v128, v128, v34, v35
	v_max3_f32 v128, v128, v36, v37
	v_max3_f32 v128, v128, v38, v39
	v_max3_f32 v128, v128, v40, v41
	v_max3_f32 v128, v128, v42, v43
	v_max3_f32 v128, v128, v44, v45
	v_max3_f32 v128, v128, v46, v47
	v_max3_f32 v128, v128, v16, v17
	v_max3_f32 v128, v128, v18, v19
	v_max3_f32 v128, v128, v20, v21
	v_max3_f32 v128, v128, v22, v23
	v_max3_f32 v128, v128, v24, v25
	v_max3_f32 v128, v128, v26, v27
	v_max3_f32 v128, v128, v28, v29
	v_max3_f32 v128, v128, v30, v31
	v_max3_f32 v128, v128, v0, v1
	v_max3_f32 v128, v128, v2, v3
	v_max3_f32 v128, v128, v4, v5
	v_max3_f32 v128, v128, v6, v7
	v_max3_f32 v128, v128, v8, v9
	v_max3_f32 v128, v128, v10, v11
	v_max3_f32 v128, v128, v12, v13
	v_max3_f32 v128, v128, v14, v15
	v_mov_b32_e32 v129, v128
	s_nop 1
	v_permlane32_swap_b32_e32 v128, v129
	v_max_f32_e32 v129, v129, v129
	v_max_f32_e32 v128, v128, v128
	v_max_f32_e32 v167, v128, v129
	v_sub_f32_e32 v112, v112, v167
	v_exp_f32_e32 v112, v112
	v_sub_f32_e32 v113, v113, v167
	v_exp_f32_e32 v113, v113
	v_sub_f32_e32 v114, v114, v167
	v_exp_f32_e32 v114, v114
	v_sub_f32_e32 v115, v115, v167
	v_exp_f32_e32 v227, v115
	v_sub_f32_e32 v115, v116, v167
	v_add_f32_e32 v128, 0, v112
	v_exp_f32_e32 v115, v115
	v_sub_f32_e32 v116, v117, v167
	v_add_f32_e32 v128, v113, v128
	v_exp_f32_e32 v116, v116
	v_sub_f32_e32 v117, v118, v167
	v_add_f32_e32 v128, v114, v128
	v_exp_f32_e32 v117, v117
	v_sub_f32_e32 v118, v119, v167
	v_add_f32_e32 v128, v227, v128
	v_exp_f32_e32 v118, v118
	v_sub_f32_e32 v120, v120, v167
	v_add_f32_e32 v128, v115, v128
	v_exp_f32_e32 v217, v120
	v_sub_f32_e32 v120, v121, v167
	v_add_f32_e32 v128, v116, v128
	v_exp_f32_e32 v221, v120
	v_sub_f32_e32 v120, v122, v167
	v_add_f32_e32 v128, v117, v128
	v_exp_f32_e32 v210, v120
	v_sub_f32_e32 v120, v123, v167
	v_add_f32_e32 v119, v118, v128
	v_exp_f32_e32 v218, v120
	v_sub_f32_e32 v120, v124, v167
	v_add_f32_e32 v119, v217, v119
	v_exp_f32_e32 v215, v120
	v_sub_f32_e32 v120, v125, v167
	v_add_f32_e32 v119, v221, v119
	v_exp_f32_e32 v220, v120
	v_sub_f32_e32 v120, v126, v167
	v_add_f32_e32 v119, v210, v119
	v_exp_f32_e32 v208, v120
	v_sub_f32_e32 v120, v127, v167
	v_add_f32_e32 v119, v218, v119
	v_exp_f32_e32 v216, v120
	v_sub_f32_e32 v96, v96, v167
	v_add_f32_e32 v119, v215, v119
	v_exp_f32_e32 v197, v96
	v_sub_f32_e32 v97, v97, v167
	v_add_f32_e32 v119, v220, v119
	v_exp_f32_e32 v201, v97
	v_sub_f32_e32 v97, v98, v167
	v_add_f32_e32 v119, v208, v119
	v_exp_f32_e32 v194, v97
; DI unsigned pk2(float lo, float hi) { bf2_t v = __builtin_convertvector((f32x2){lo, hi}, bf2_t); return __builtin_bit_cast(unsigned, v); }
; DI void xattn_unit(const bf16_t* __restrict__ Qg, const bf16_t* __restrict__ Kg, const bf16_t* __restrict__ Vg, bf16_t* __restrict__ Og, lds_t* shm) {
;     ...
; #pragma unroll
;   for (int t = 0; t < 4; ++t)
; #pragma unroll
;     for (int kb = 0; kb < 2; ++kb)
; #pragma unroll
;       for (int s2 = 0; s2 < 2; ++s2) {
;         float e[8];
; #pragma unroll
;         for (int j = 0; j < 8; ++j) { e[j] = __builtin_amdgcn_exp2f(S[t][kb][8 * s2 + j] - mx); rs += e[j]; }
;         u32x4 w; w.x = pk2(e[0], e[1]); w.y = pk2(e[2], e[3]); w.z = pk2(e[4], e[5]); w.w = pk2(e[6], e[7]);
;         P[t][kb][s2] = __builtin_bit_cast(bf16x8, w);
;       }
	v_sub_f32_e32 v97, v99, v167
	v_add_f32_e32 v119, v216, v119
	v_exp_f32_e32 v198, v97
	v_sub_f32_e32 v97, v100, v167
	v_add_f32_e32 v96, v197, v119
	v_exp_f32_e32 v195, v97
	v_sub_f32_e32 v97, v101, v167
	v_add_f32_e32 v96, v201, v96
	v_exp_f32_e32 v199, v97
	v_sub_f32_e32 v97, v102, v167
	v_add_f32_e32 v96, v194, v96
	v_exp_f32_e32 v191, v97
	v_sub_f32_e32 v97, v103, v167
	v_add_f32_e32 v96, v198, v96
	v_exp_f32_e32 v193, v97
	v_sub_f32_e32 v97, v104, v167
	v_add_f32_e32 v96, v195, v96
	v_exp_f32_e32 v179, v97
	v_sub_f32_e32 v97, v105, v167
	v_add_f32_e32 v96, v199, v96
	v_exp_f32_e32 v183, v97
	v_sub_f32_e32 v97, v106, v167
	v_add_f32_e32 v96, v191, v96
	v_exp_f32_e32 v177, v97
	v_sub_f32_e32 v97, v107, v167
	v_add_f32_e32 v96, v193, v96
	v_exp_f32_e32 v180, v97
	v_sub_f32_e32 v97, v108, v167
	v_add_f32_e32 v96, v179, v96
	v_exp_f32_e32 v178, v97
	v_sub_f32_e32 v97, v109, v167
	v_add_f32_e32 v96, v183, v96
	v_exp_f32_e32 v181, v97
	v_sub_f32_e32 v97, v110, v167
	v_add_f32_e32 v96, v177, v96
	v_exp_f32_e32 v174, v97
	v_sub_f32_e32 v97, v111, v167
	v_add_f32_e32 v96, v180, v96
	v_exp_f32_e32 v176, v97
	v_sub_f32_e32 v80, v80, v167
	v_add_f32_e32 v96, v178, v96
	v_exp_f32_e32 v80, v80
	v_sub_f32_e32 v81, v81, v167
	v_add_f32_e32 v96, v181, v96
	v_exp_f32_e32 v81, v81
	v_sub_f32_e32 v82, v82, v167
	v_add_f32_e32 v96, v174, v96
	v_exp_f32_e32 v82, v82
	v_sub_f32_e32 v83, v83, v167
	v_add_f32_e32 v96, v176, v96
	v_exp_f32_e32 v83, v83
	v_sub_f32_e32 v84, v84, v167
	v_add_f32_e32 v96, v80, v96
	v_exp_f32_e32 v84, v84
	v_sub_f32_e32 v85, v85, v167
	v_add_f32_e32 v96, v81, v96
	v_exp_f32_e32 v85, v85
	v_sub_f32_e32 v86, v86, v167
	v_add_f32_e32 v96, v82, v96
	v_exp_f32_e32 v86, v86
	v_sub_f32_e32 v87, v87, v167
	v_add_f32_e32 v96, v83, v96
	v_exp_f32_e32 v87, v87
	v_cvt_pk_bf16_f32 v128, v80, v81
	v_sub_f32_e32 v80, v88, v167
	v_add_f32_e32 v96, v84, v96
	v_cvt_pk_bf16_f32 v129, v82, v83
	v_exp_f32_e32 v80, v80
	v_sub_f32_e32 v82, v89, v167
	v_add_f32_e32 v96, v85, v96
	v_exp_f32_e32 v82, v82
	v_sub_f32_e32 v83, v90, v167
	v_add_f32_e32 v96, v86, v96
	v_cvt_pk_bf16_f32 v130, v84, v85
	v_exp_f32_e32 v83, v83
	v_sub_f32_e32 v84, v91, v167
	v_add_f32_e32 v96, v87, v96
	v_exp_f32_e32 v84, v84
	v_sub_f32_e32 v85, v92, v167
	v_cvt_pk_bf16_f32 v131, v86, v87
	v_add_f32_e32 v81, v80, v96
	v_exp_f32_e32 v85, v85
	v_sub_f32_e32 v86, v93, v167
	v_add_f32_e32 v81, v82, v81
	v_exp_f32_e32 v86, v86
	v_sub_f32_e32 v87, v94, v167
	v_add_f32_e32 v81, v83, v81
	v_exp_f32_e32 v87, v87
	v_sub_f32_e32 v88, v95, v167
	v_add_f32_e32 v81, v84, v81
	v_exp_f32_e32 v88, v88
	v_sub_f32_e32 v64, v64, v167
	v_add_f32_e32 v81, v85, v81
	v_exp_f32_e32 v64, v64
	v_sub_f32_e32 v65, v65, v167
	v_add_f32_e32 v81, v86, v81
	v_exp_f32_e32 v65, v65
	v_sub_f32_e32 v66, v66, v167
	v_add_f32_e32 v81, v87, v81
	v_exp_f32_e32 v66, v66
	v_sub_f32_e32 v67, v67, v167
	v_add_f32_e32 v81, v88, v81
	v_exp_f32_e32 v67, v67
	v_sub_f32_e32 v68, v68, v167
	v_cvt_pk_bf16_f32 v132, v80, v82
	v_add_f32_e32 v80, v64, v81
	v_exp_f32_e32 v68, v68
	v_sub_f32_e32 v69, v69, v167
	v_add_f32_e32 v80, v65, v80
	v_exp_f32_e32 v69, v69
	v_sub_f32_e32 v70, v70, v167
	v_add_f32_e32 v80, v66, v80
	v_exp_f32_e32 v70, v70
	v_sub_f32_e32 v71, v71, v167
	v_add_f32_e32 v80, v67, v80
	v_exp_f32_e32 v71, v71
	v_cvt_pk_bf16_f32 v136, v64, v65
	v_sub_f32_e32 v64, v72, v167
	v_add_f32_e32 v80, v68, v80
	v_cvt_pk_bf16_f32 v137, v66, v67
	v_exp_f32_e32 v64, v64
	v_sub_f32_e32 v66, v73, v167
	v_add_f32_e32 v80, v69, v80
	v_exp_f32_e32 v66, v66
	v_sub_f32_e32 v67, v74, v167
	v_add_f32_e32 v80, v70, v80
	v_cvt_pk_bf16_f32 v138, v68, v69
	v_exp_f32_e32 v67, v67
	v_sub_f32_e32 v68, v75, v167
	v_add_f32_e32 v80, v71, v80
	v_exp_f32_e32 v68, v68
	v_sub_f32_e32 v69, v76, v167
	v_cvt_pk_bf16_f32 v139, v70, v71
	v_add_f32_e32 v65, v64, v80
	v_exp_f32_e32 v69, v69
	v_sub_f32_e32 v70, v77, v167
	v_add_f32_e32 v65, v66, v65
	v_exp_f32_e32 v70, v70
	v_sub_f32_e32 v71, v78, v167
	v_add_f32_e32 v65, v67, v65
	v_exp_f32_e32 v71, v71
	v_sub_f32_e32 v72, v79, v167
	v_add_f32_e32 v65, v68, v65
	v_exp_f32_e32 v72, v72
	v_sub_f32_e32 v48, v48, v167
	v_add_f32_e32 v65, v69, v65
	v_exp_f32_e32 v48, v48
	v_sub_f32_e32 v49, v49, v167
	v_add_f32_e32 v65, v70, v65
	v_exp_f32_e32 v49, v49
	v_sub_f32_e32 v50, v50, v167
	v_add_f32_e32 v65, v71, v65
	v_exp_f32_e32 v50, v50
	v_sub_f32_e32 v51, v51, v167
	v_add_f32_e32 v65, v72, v65
	v_exp_f32_e32 v51, v51
	v_sub_f32_e32 v52, v52, v167
	v_cvt_pk_bf16_f32 v156, v64, v66
	v_add_f32_e32 v64, v48, v65
	v_exp_f32_e32 v52, v52
	v_sub_f32_e32 v53, v53, v167
	v_add_f32_e32 v64, v49, v64
	v_exp_f32_e32 v53, v53
	v_sub_f32_e32 v54, v54, v167
	v_add_f32_e32 v64, v50, v64
	v_exp_f32_e32 v54, v54
	v_sub_f32_e32 v55, v55, v167
	v_add_f32_e32 v64, v51, v64
	v_exp_f32_e32 v55, v55
	v_cvt_pk_bf16_f32 v152, v48, v49
	v_sub_f32_e32 v48, v56, v167
	v_add_f32_e32 v64, v52, v64
	v_cvt_pk_bf16_f32 v153, v50, v51
	v_exp_f32_e32 v48, v48
	v_sub_f32_e32 v50, v57, v167
	v_add_f32_e32 v64, v53, v64
	v_exp_f32_e32 v50, v50
	v_sub_f32_e32 v51, v58, v167
	v_add_f32_e32 v64, v54, v64
	v_cvt_pk_bf16_f32 v154, v52, v53
	v_exp_f32_e32 v51, v51
	v_sub_f32_e32 v52, v59, v167
	v_add_f32_e32 v64, v55, v64
	v_exp_f32_e32 v52, v52
	v_sub_f32_e32 v53, v60, v167
	v_cvt_pk_bf16_f32 v155, v54, v55
	v_add_f32_e32 v49, v48, v64
	v_exp_f32_e32 v53, v53
	v_sub_f32_e32 v54, v61, v167
	v_add_f32_e32 v49, v50, v49
	v_exp_f32_e32 v54, v54
	v_sub_f32_e32 v55, v62, v167
	v_add_f32_e32 v49, v51, v49
	v_exp_f32_e32 v55, v55
	v_sub_f32_e32 v56, v63, v167
	v_add_f32_e32 v49, v52, v49
	v_exp_f32_e32 v56, v56
	v_sub_f32_e32 v32, v32, v167
	v_add_f32_e32 v49, v53, v49
; DI unsigned pk2(float lo, float hi) { bf2_t v = __builtin_convertvector((f32x2){lo, hi}, bf2_t); return __builtin_bit_cast(unsigned, v); }
; DI void xattn_unit(const bf16_t* __restrict__ Qg, const bf16_t* __restrict__ Kg, const bf16_t* __restrict__ Vg, bf16_t* __restrict__ Og, lds_t* shm) {
;     ...
; #pragma unroll
;   for (int t = 0; t < 4; ++t)
; #pragma unroll
;     for (int kb = 0; kb < 2; ++kb)
; #pragma unroll
;       for (int s2 = 0; s2 < 2; ++s2) {
;         float e[8];
; #pragma unroll
;         for (int j = 0; j < 8; ++j) { e[j] = __builtin_amdgcn_exp2f(S[t][kb][8 * s2 + j] - mx); rs += e[j]; }
;         u32x4 w; w.x = pk2(e[0], e[1]); w.y = pk2(e[2], e[3]); w.z = pk2(e[4], e[5]); w.w = pk2(e[6], e[7]);
;         P[t][kb][s2] = __builtin_bit_cast(bf16x8, w);
;       }
;   const float l = rs + __shfl_xor(rs, 32);
;   __builtin_amdgcn_sched_barrier(0);
;   __syncthreads();
	v_exp_f32_e32 v32, v32
	v_sub_f32_e32 v33, v33, v167
	v_add_f32_e32 v49, v54, v49
	v_exp_f32_e32 v33, v33
	v_sub_f32_e32 v34, v34, v167
	v_add_f32_e32 v49, v55, v49
	v_exp_f32_e32 v34, v34
	v_sub_f32_e32 v35, v35, v167
	v_add_f32_e32 v49, v56, v49
	v_exp_f32_e32 v35, v35
	v_sub_f32_e32 v36, v36, v167
	v_cvt_pk_bf16_f32 v148, v48, v50
	v_add_f32_e32 v48, v32, v49
	v_exp_f32_e32 v36, v36
	v_sub_f32_e32 v37, v37, v167
	v_add_f32_e32 v48, v33, v48
	v_exp_f32_e32 v37, v37
	v_sub_f32_e32 v38, v38, v167
	v_add_f32_e32 v48, v34, v48
	v_exp_f32_e32 v38, v38
	v_sub_f32_e32 v39, v39, v167
	v_add_f32_e32 v48, v35, v48
	v_exp_f32_e32 v39, v39
	v_cvt_pk_bf16_f32 v140, v32, v33
	v_sub_f32_e32 v32, v40, v167
	v_add_f32_e32 v48, v36, v48
	v_cvt_pk_bf16_f32 v141, v34, v35
	v_exp_f32_e32 v32, v32
	v_sub_f32_e32 v34, v41, v167
	v_add_f32_e32 v48, v37, v48
	v_exp_f32_e32 v34, v34
	v_sub_f32_e32 v35, v42, v167
	v_add_f32_e32 v48, v38, v48
	v_cvt_pk_bf16_f32 v142, v36, v37
	v_exp_f32_e32 v35, v35
	v_sub_f32_e32 v36, v43, v167
	v_add_f32_e32 v48, v39, v48
	v_exp_f32_e32 v36, v36
	v_sub_f32_e32 v37, v44, v167
	v_cvt_pk_bf16_f32 v143, v38, v39
	v_add_f32_e32 v33, v32, v48
	v_exp_f32_e32 v37, v37
	v_sub_f32_e32 v38, v45, v167
	v_add_f32_e32 v33, v34, v33
	v_exp_f32_e32 v38, v38
	v_sub_f32_e32 v39, v46, v167
	v_add_f32_e32 v33, v35, v33
	v_exp_f32_e32 v39, v39
	v_sub_f32_e32 v40, v47, v167
	v_add_f32_e32 v33, v36, v33
	v_exp_f32_e32 v40, v40
	v_sub_f32_e32 v16, v16, v167
	v_add_f32_e32 v33, v37, v33
	v_exp_f32_e32 v171, v16
	v_sub_f32_e32 v17, v17, v167
	v_add_f32_e32 v33, v38, v33
	v_exp_f32_e32 v172, v17
	v_sub_f32_e32 v17, v18, v167
	v_add_f32_e32 v33, v39, v33
	v_exp_f32_e32 v173, v17
	v_sub_f32_e32 v17, v19, v167
	v_add_f32_e32 v33, v40, v33
	v_exp_f32_e32 v175, v17
	v_sub_f32_e32 v17, v20, v167
	v_add_f32_e32 v16, v171, v33
	v_exp_f32_e32 v182, v17
	v_sub_f32_e32 v17, v21, v167
	v_add_f32_e32 v16, v172, v16
	v_exp_f32_e32 v184, v17
	v_sub_f32_e32 v17, v22, v167
	v_add_f32_e32 v16, v173, v16
	v_exp_f32_e32 v185, v17
	v_sub_f32_e32 v17, v23, v167
	v_add_f32_e32 v16, v175, v16
	v_exp_f32_e32 v186, v17
	v_sub_f32_e32 v17, v24, v167
	v_add_f32_e32 v16, v182, v16
	v_exp_f32_e32 v187, v17
	v_sub_f32_e32 v17, v25, v167
	v_add_f32_e32 v16, v184, v16
	v_exp_f32_e32 v188, v17
	v_sub_f32_e32 v17, v26, v167
	v_add_f32_e32 v16, v185, v16
	v_exp_f32_e32 v189, v17
	v_sub_f32_e32 v17, v27, v167
	v_add_f32_e32 v16, v186, v16
	v_exp_f32_e32 v190, v17
	v_sub_f32_e32 v17, v28, v167
	v_add_f32_e32 v16, v187, v16
	v_exp_f32_e32 v192, v17
	v_sub_f32_e32 v17, v29, v167
	v_add_f32_e32 v16, v188, v16
	v_exp_f32_e32 v196, v17
	v_sub_f32_e32 v17, v30, v167
	v_add_f32_e32 v16, v189, v16
	v_exp_f32_e32 v200, v17
	v_sub_f32_e32 v17, v31, v167
	v_add_f32_e32 v16, v190, v16
	v_exp_f32_e32 v202, v17
	v_sub_f32_e32 v0, v0, v167
	v_add_f32_e32 v16, v192, v16
	v_exp_f32_e32 v203, v0
	v_sub_f32_e32 v1, v1, v167
	v_add_f32_e32 v16, v196, v16
	v_exp_f32_e32 v204, v1
	v_sub_f32_e32 v1, v2, v167
	v_add_f32_e32 v16, v200, v16
	v_exp_f32_e32 v205, v1
	v_sub_f32_e32 v1, v3, v167
	v_add_f32_e32 v16, v202, v16
	v_exp_f32_e32 v206, v1
	v_sub_f32_e32 v1, v4, v167
	v_add_f32_e32 v0, v203, v16
	v_exp_f32_e32 v207, v1
	v_sub_f32_e32 v1, v5, v167
	v_add_f32_e32 v0, v204, v0
	v_exp_f32_e32 v209, v1
	v_sub_f32_e32 v1, v6, v167
	v_add_f32_e32 v0, v205, v0
	v_exp_f32_e32 v211, v1
	v_sub_f32_e32 v1, v7, v167
	v_add_f32_e32 v0, v206, v0
	v_exp_f32_e32 v219, v1
	v_sub_f32_e32 v1, v8, v167
	v_add_f32_e32 v0, v207, v0
	v_exp_f32_e32 v222, v1
	v_sub_f32_e32 v1, v9, v167
	v_add_f32_e32 v0, v209, v0
	v_exp_f32_e32 v223, v1
	v_sub_f32_e32 v1, v10, v167
	v_add_f32_e32 v0, v211, v0
	v_exp_f32_e32 v224, v1
	v_sub_f32_e32 v1, v11, v167
	v_add_f32_e32 v0, v219, v0
	v_exp_f32_e32 v225, v1
	v_sub_f32_e32 v1, v12, v167
	v_add_f32_e32 v0, v222, v0
	v_exp_f32_e32 v226, v1
	v_sub_f32_e32 v1, v13, v167
	v_add_f32_e32 v0, v223, v0
	v_exp_f32_e32 v228, v1
	v_sub_f32_e32 v1, v14, v167
	v_add_f32_e32 v0, v224, v0
	v_exp_f32_e32 v229, v1
	v_sub_f32_e32 v1, v15, v167
	v_add_f32_e32 v0, v225, v0
	v_exp_f32_e32 v230, v1
	v_add_f32_e32 v0, v226, v0
	v_add_f32_e32 v0, v228, v0
	v_add_f32_e32 v0, v229, v0
	v_add_f32_e32 v167, v230, v0
	v_cvt_pk_bf16_f32 v133, v83, v84
	v_cvt_pk_bf16_f32 v134, v85, v86
	v_cvt_pk_bf16_f32 v135, v87, v88
	v_cvt_pk_bf16_f32 v157, v67, v68
	v_cvt_pk_bf16_f32 v158, v69, v70
	v_cvt_pk_bf16_f32 v159, v71, v72
	v_cvt_pk_bf16_f32 v149, v51, v52
	v_cvt_pk_bf16_f32 v150, v53, v54
	v_cvt_pk_bf16_f32 v151, v55, v56
	v_cvt_pk_bf16_f32 v144, v32, v34
	v_cvt_pk_bf16_f32 v145, v35, v36
	v_cvt_pk_bf16_f32 v146, v37, v38
	v_cvt_pk_bf16_f32 v147, v39, v40
	ds_bpermute_b32 v168, v213, v167
	s_waitcnt lgkmcnt(0)
	s_barrier
; #define MFMA32(a, b, c) __builtin_amdgcn_mfma_f32_32x32x16_bf16((a), (b), (c), 0, 0, 0)
; DI void xattn_unit(const bf16_t* __restrict__ Qg, const bf16_t* __restrict__ Kg, const bf16_t* __restrict__ Vg, bf16_t* __restrict__ Og, lds_t* shm) {
;     ...
;   __builtin_amdgcn_sched_barrier(0);
;   __syncthreads();
;   __builtin_amdgcn_sched_barrier(0);
; #pragma unroll
;   for (int t = 1; t < 4; ++t) issue_tile(Vg, t, t * 32768);
;   f32x16 O[NC];
; #pragma unroll
;   for (int c = 0; c < NC; ++c)
; #pragma unroll
;     for (int i = 0; i < 16; ++i) O[c][i] = 0.f;
; #pragma unroll
;   for (int t = 0; t < 4; ++t) {
;     if (t == 1) { __builtin_amdgcn_sched_barrier(0); asm volatile("s_waitcnt vmcnt(0)" ::: "memory"); __syncthreads(); __builtin_amdgcn_sched_barrier(0); }
;     const unsigned vbase = (t == 0) ? 131072u : (unsigned)t * 32768u;
; #pragma unroll
;     for (int ks = 0; ks < 4; ++ks)
; #pragma unroll
;       for (int c = 0; c < NC; ++c) {
;         const unsigned vo = vbase + (c >> 2) * 16384 + 512 * (c & 3) + 4096 * ks;
;         const bf16x8 vf = tr_pair(shm + vo + va0, shm + vo + 2048 + va1);
;         O[c] = MFMA32(vf, P[t][ks >> 1][ks & 1], O[c]);
;       }
	s_add_u32 s38, s36, 0x40800
	s_mov_b32 m0, s67
	s_addc_u32 s39, s37, 0
	global_load_lds_dwordx4 v160, s[38:39]
	s_mov_b32 m0, s0
	v_add_u32_e32 v2, s14, v170
	global_load_lds_dwordx4 v162, s[38:39]
	s_add_u32 s38, s36, 0x40900
	s_addc_u32 s39, s37, 0
	s_mov_b32 m0, s1
	s_add_u32 s0, s36, 0x80800
	global_load_lds_dwordx4 v160, s[38:39]
	s_mov_b32 m0, vcc_lo
	s_addc_u32 s1, s37, 0
	global_load_lds_dwordx4 v162, s[38:39]
	s_mov_b32 m0, vcc_hi
	v_cvt_pk_bf16_f32 v0, v112, v113
	global_load_lds_dwordx4 v160, s[0:1]
	s_mov_b32 m0, s28
	v_cvt_pk_bf16_f32 v1, v114, v227
	global_load_lds_dwordx4 v162, s[0:1]
	s_add_u32 s0, s36, 0x80900
	s_addc_u32 s1, s37, 0
	s_mov_b32 m0, s29
	v_cvt_pk_bf16_f32 v232, v217, v221
	global_load_lds_dwordx4 v160, s[0:1]
	s_mov_b32 m0, s68
	v_cvt_pk_bf16_f32 v233, v210, v218
	global_load_lds_dwordx4 v162, s[0:1]
	s_add_u32 s0, s36, 0xc0800
	s_addc_u32 s1, s37, 0
	s_mov_b32 m0, s69
	v_cvt_pk_bf16_f32 v234, v215, v220
	global_load_lds_dwordx4 v160, s[0:1]
	s_mov_b32 m0, s76
	v_cvt_pk_bf16_f32 v235, v208, v216
	global_load_lds_dwordx4 v162, s[0:1]
	s_add_u32 s0, s36, 0xc0900
	s_addc_u32 s1, s37, 0
	s_mov_b32 m0, s77
	s_nop 0
	global_load_lds_dwordx4 v160, s[0:1]
	s_mov_b32 m0, s78
	v_and_b32_e32 v160, 8, v169
	global_load_lds_dwordx4 v162, s[0:1]
	v_readlane_b32 s0, v254, 14
	v_add3_u32 v2, v2, v166, v160
	s_nop 0
	v_add_u32_e32 v3, s0, v170
	v_add3_u32 v3, v3, v165, v160
	ds_read_b64_tr_b16 v[4:5], v2
	ds_read_b64_tr_b16 v[6:7], v3
	v_readlane_b32 s0, v254, 25
	v_cvt_pk_bf16_f32 v2, v115, v116
	v_cvt_pk_bf16_f32 v3, v117, v118
	v_add_u32_e32 v8, s0, v170
	v_readlane_b32 s0, v254, 26
	v_add3_u32 v8, v8, v166, v160
	s_waitcnt lgkmcnt(0)
	v_mfma_f32_32x32x16_bf16 v[112:127], v[4:7], v[0:3], 0
	v_add_u32_e32 v9, s0, v170
	v_readlane_b32 s0, v254, 27
	v_add3_u32 v10, v9, v165, v160
	ds_read_b64_tr_b16 v[8:9], v8
	ds_read_b64_tr_b16 v[10:11], v10
	v_add_u32_e32 v4, s0, v170
	v_readlane_b32 s0, v254, 28
	v_add3_u32 v4, v4, v166, v160
	s_waitcnt lgkmcnt(0)
	v_mfma_f32_32x32x16_bf16 v[96:111], v[8:11], v[0:3], 0
	v_add_u32_e32 v5, s0, v170
	v_add3_u32 v6, v5, v165, v160
	ds_read_b64_tr_b16 v[4:5], v4
	ds_read_b64_tr_b16 v[6:7], v6
	v_readlane_b32 s0, v254, 29
	s_nop 1
	v_add_u32_e32 v8, s0, v170
	v_readlane_b32 s0, v254, 30
	v_add3_u32 v8, v8, v166, v160
	s_waitcnt lgkmcnt(0)
	v_mfma_f32_32x32x16_bf16 v[80:95], v[4:7], v[0:3], 0
	v_add_u32_e32 v9, s0, v170
	v_readlane_b32 s0, v254, 31
	v_add3_u32 v10, v9, v165, v160
	ds_read_b64_tr_b16 v[8:9], v8
	ds_read_b64_tr_b16 v[10:11], v10
	v_add_u32_e32 v4, s0, v170
	v_readlane_b32 s0, v254, 32
	v_add3_u32 v4, v4, v166, v160
	s_waitcnt lgkmcnt(0)
	v_mfma_f32_32x32x16_bf16 v[64:79], v[8:11], v[0:3], 0
	v_add_u32_e32 v5, s0, v170
	v_add3_u32 v6, v5, v165, v160
	ds_read_b64_tr_b16 v[4:5], v4
	ds_read_b64_tr_b16 v[6:7], v6
	v_readlane_b32 s0, v254, 33
	s_nop 1
	v_add_u32_e32 v8, s0, v170
	v_readlane_b32 s0, v254, 34
	v_add3_u32 v8, v8, v166, v160
	s_waitcnt lgkmcnt(0)
	v_mfma_f32_32x32x16_bf16 v[48:63], v[4:7], v[0:3], 0
	v_add_u32_e32 v9, s0, v170
	v_readlane_b32 s0, v254, 35
	v_add3_u32 v10, v9, v165, v160
	ds_read_b64_tr_b16 v[8:9], v8
	ds_read_b64_tr_b16 v[10:11], v10
	v_add_u32_e32 v4, s0, v170
	v_readlane_b32 s0, v254, 36
	v_add3_u32 v4, v4, v166, v160
	s_waitcnt lgkmcnt(0)
	v_mfma_f32_32x32x16_bf16 v[32:47], v[8:11], v[0:3], 0
	v_add_u32_e32 v5, s0, v170
	v_add3_u32 v6, v5, v165, v160
	ds_read_b64_tr_b16 v[4:5], v4
	ds_read_b64_tr_b16 v[6:7], v6
	v_readlane_b32 s0, v254, 37
	s_nop 1
	v_add_u32_e32 v8, s0, v170
	v_readlane_b32 s0, v254, 38
	s_waitcnt lgkmcnt(0)
	v_mfma_f32_32x32x16_bf16 v[16:31], v[4:7], v[0:3], 0
	v_add3_u32 v8, v8, v166, v160
	v_add_u32_e32 v9, s0, v170
	v_readlane_b32 s0, v254, 39
	v_add3_u32 v10, v9, v165, v160
	ds_read_b64_tr_b16 v[8:9], v8
	ds_read_b64_tr_b16 v[10:11], v10
	v_add_u32_e32 v4, s0, v170
	v_readlane_b32 s0, v254, 40
	v_add3_u32 v4, v4, v166, v160
	s_nop 0
	v_add_u32_e32 v5, s0, v170
	v_readlane_b32 s0, v254, 41
	v_add3_u32 v5, v5, v165, v160
	ds_read_b64_tr_b16 v[236:237], v4
	ds_read_b64_tr_b16 v[238:239], v5
	v_add_u32_e32 v162, s0, v170
	v_readlane_b32 s0, v254, 42
	v_add3_u32 v162, v162, v166, v160
	s_waitcnt lgkmcnt(0)
	v_mfma_f32_32x32x16_bf16 v[112:127], v[236:239], v[232:235], v[112:127]
	v_add_u32_e32 v169, s0, v170
	v_add3_u32 v169, v169, v165, v160
	ds_read_b64_tr_b16 v[240:241], v162
	ds_read_b64_tr_b16 v[242:243], v169
	v_readlane_b32 s0, v254, 43
	s_nop 1
	v_add_u32_e32 v162, s0, v170
	v_readlane_b32 s0, v254, 44
	v_add3_u32 v162, v162, v166, v160
	s_waitcnt lgkmcnt(0)
	v_mfma_f32_32x32x16_bf16 v[96:111], v[240:243], v[232:235], v[96:111]
	v_add_u32_e32 v169, s0, v170
	v_readlane_b32 s0, v254, 45
	v_add3_u32 v169, v169, v165, v160
	ds_read_b64_tr_b16 v[236:237], v162
	ds_read_b64_tr_b16 v[238:239], v169
	v_add_u32_e32 v162, s0, v170
	v_readlane_b32 s0, v254, 46
	v_add3_u32 v162, v162, v166, v160
	s_waitcnt lgkmcnt(0)
	v_mfma_f32_32x32x16_bf16 v[80:95], v[236:239], v[232:235], v[80:95]
	v_add_u32_e32 v169, s0, v170
	v_add3_u32 v169, v169, v165, v160
	ds_read_b64_tr_b16 v[240:241], v162
	ds_read_b64_tr_b16 v[242:243], v169
	v_readlane_b32 s0, v254, 47
	s_nop 1
	v_add_u32_e32 v162, s0, v170
	v_readlane_b32 s0, v254, 48
	v_add3_u32 v162, v162, v166, v160
	s_waitcnt lgkmcnt(0)
	v_mfma_f32_32x32x16_bf16 v[64:79], v[240:243], v[232:235], v[64:79]
	v_add_u32_e32 v169, s0, v170
	v_readlane_b32 s0, v254, 49
	v_add3_u32 v169, v169, v165, v160
	ds_read_b64_tr_b16 v[236:237], v162
	ds_read_b64_tr_b16 v[238:239], v169
	v_add_u32_e32 v162, s0, v170
	v_readlane_b32 s0, v254, 50
	v_add3_u32 v162, v162, v166, v160
	v_mfma_f32_32x32x16_bf16 v[0:15], v[8:11], v[0:3], 0
	v_add_u32_e32 v169, s0, v170
	v_add3_u32 v169, v169, v165, v160
	ds_read_b64_tr_b16 v[240:241], v162
	ds_read_b64_tr_b16 v[242:243], v169
	v_readlane_b32 s0, v254, 51
	s_nop 1
	v_add_u32_e32 v162, s0, v170
	v_readlane_b32 s0, v254, 52
	v_add3_u32 v162, v162, v166, v160
	s_waitcnt lgkmcnt(0)
; #define MFMA32(a, b, c) __builtin_amdgcn_mfma_f32_32x32x16_bf16((a), (b), (c), 0, 0, 0)
; DI void xattn_unit(const bf16_t* __restrict__ Qg, const bf16_t* __restrict__ Kg, const bf16_t* __restrict__ Vg, bf16_t* __restrict__ Og, lds_t* shm) {
;     ...
;   for (int t = 0; t < 4; ++t) {
;     if (t == 1) { __builtin_amdgcn_sched_barrier(0); asm volatile("s_waitcnt vmcnt(0)" ::: "memory"); __syncthreads(); __builtin_amdgcn_sched_barrier(0); }
;     const unsigned vbase = (t == 0) ? 131072u : (unsigned)t * 32768u;
; #pragma unroll
;     for (int ks = 0; ks < 4; ++ks)
; #pragma unroll
;       for (int c = 0; c < NC; ++c) {
;         const unsigned vo = vbase + (c >> 2) * 16384 + 512 * (c & 3) + 4096 * ks;
;         const bf16x8 vf = tr_pair(shm + vo + va0, shm + vo + 2048 + va1);
;         O[c] = MFMA32(vf, P[t][ks >> 1][ks & 1], O[c]);
;       }
	v_mfma_f32_32x32x16_bf16 v[32:47], v[240:243], v[232:235], v[32:47]
	v_add_u32_e32 v169, s0, v170
	v_readlane_b32 s0, v254, 53
	v_add3_u32 v169, v169, v165, v160
	ds_read_b64_tr_b16 v[244:245], v162
	ds_read_b64_tr_b16 v[246:247], v169
	v_add_u32_e32 v162, s0, v170
	v_readlane_b32 s0, v254, 54
	v_add3_u32 v162, v162, v166, v160
	s_waitcnt lgkmcnt(0)
	v_mfma_f32_32x32x16_bf16 v[16:31], v[244:247], v[232:235], v[16:31]
	v_add_u32_e32 v169, s0, v170
	v_add3_u32 v169, v169, v165, v160
	ds_read_b64_tr_b16 v[240:241], v162
	ds_read_b64_tr_b16 v[242:243], v169
	v_readlane_b32 s0, v254, 55
	s_nop 1
	v_add_u32_e32 v162, s0, v170
	v_readlane_b32 s0, v254, 56
	v_add3_u32 v162, v162, v166, v160
	v_mfma_f32_32x32x16_bf16 v[48:63], v[236:239], v[232:235], v[48:63]
	v_add_u32_e32 v169, s0, v170
	v_readlane_b32 s0, v254, 57
	v_add3_u32 v169, v169, v165, v160
	ds_read_b64_tr_b16 v[244:245], v162
	ds_read_b64_tr_b16 v[246:247], v169
	v_add_u32_e32 v162, s0, v170
	v_readlane_b32 s0, v254, 58
	v_add3_u32 v162, v162, v166, v160
	s_waitcnt lgkmcnt(0)
	v_mfma_f32_32x32x16_bf16 v[0:15], v[240:243], v[232:235], v[0:15]
	v_add_u32_e32 v169, s0, v170
	v_add3_u32 v169, v169, v165, v160
	ds_read_b64_tr_b16 v[232:233], v162
	ds_read_b64_tr_b16 v[234:235], v169
	v_readlane_b32 s0, v254, 59
	v_cvt_pk_bf16_f32 v236, v197, v201
	v_cvt_pk_bf16_f32 v237, v194, v198
	v_add_u32_e32 v162, s0, v170
	v_readlane_b32 s0, v254, 60
	v_cvt_pk_bf16_f32 v238, v195, v199
	v_cvt_pk_bf16_f32 v239, v191, v193
	v_add3_u32 v162, v162, v166, v160
	v_add_u32_e32 v169, s0, v170
	v_readlane_b32 s0, v254, 61
	s_waitcnt lgkmcnt(0)
	v_mfma_f32_32x32x16_bf16 v[96:111], v[232:235], v[236:239], v[96:111]
	v_add3_u32 v169, v169, v165, v160
	ds_read_b64_tr_b16 v[232:233], v162
	ds_read_b64_tr_b16 v[234:235], v169
	v_add_u32_e32 v162, s0, v170
	v_readlane_b32 s0, v254, 62
	v_add3_u32 v162, v162, v166, v160
	s_nop 0
	v_add_u32_e32 v169, s0, v170
	v_add3_u32 v169, v169, v165, v160
	ds_read_b64_tr_b16 v[240:241], v162
	ds_read_b64_tr_b16 v[242:243], v169
	v_readlane_b32 s0, v254, 63
	s_waitcnt lgkmcnt(0)
	v_mfma_f32_32x32x16_bf16 v[80:95], v[232:235], v[236:239], v[80:95]
	v_add_u32_e32 v162, s0, v170
	v_readlane_b32 s0, v255, 0
	v_add3_u32 v162, v162, v166, v160
	s_nop 0
	v_add_u32_e32 v169, s0, v170
	v_readlane_b32 s0, v255, 1
	v_add3_u32 v169, v169, v165, v160
	ds_read_b64_tr_b16 v[232:233], v162
	ds_read_b64_tr_b16 v[234:235], v169
	v_add_u32_e32 v162, s0, v170
	v_readlane_b32 s0, v255, 2
	v_add3_u32 v162, v162, v166, v160
	v_mfma_f32_32x32x16_bf16 v[64:79], v[240:243], v[236:239], v[64:79]
	v_add_u32_e32 v169, s0, v170
	v_add3_u32 v169, v169, v165, v160
	ds_read_b64_tr_b16 v[240:241], v162
	ds_read_b64_tr_b16 v[242:243], v169
	v_readlane_b32 s0, v255, 3
	s_nop 1
	v_add_u32_e32 v162, s0, v170
	v_readlane_b32 s0, v255, 4
	v_add3_u32 v162, v162, v166, v160
	v_mfma_f32_32x32x16_bf16 v[112:127], v[244:247], v[236:239], v[112:127]
	v_add_u32_e32 v169, s0, v170
	v_readlane_b32 s0, v255, 5
	v_add3_u32 v169, v169, v165, v160
	ds_read_b64_tr_b16 v[244:245], v162
	ds_read_b64_tr_b16 v[246:247], v169
	v_add_u32_e32 v162, s0, v170
	v_readlane_b32 s0, v255, 6
	v_add3_u32 v162, v162, v166, v160
	s_waitcnt lgkmcnt(0)
	v_mfma_f32_32x32x16_bf16 v[32:47], v[240:243], v[236:239], v[32:47]
	v_add_u32_e32 v169, s0, v170
	v_add3_u32 v169, v169, v165, v160
	ds_read_b64_tr_b16 v[240:241], v162
	ds_read_b64_tr_b16 v[242:243], v169
	v_readlane_b32 s0, v255, 7
	s_nop 1
	v_add_u32_e32 v162, s0, v170
	v_readlane_b32 s0, v255, 8
	v_add3_u32 v162, v162, v166, v160
	v_mfma_f32_32x32x16_bf16 v[48:63], v[232:235], v[236:239], v[48:63]
	v_add_u32_e32 v169, s0, v170
	v_readlane_b32 s0, v255, 9
	v_cvt_pk_bf16_f32 v232, v179, v183
	v_cvt_pk_bf16_f32 v233, v177, v180
	v_cvt_pk_bf16_f32 v234, v178, v181
	v_add3_u32 v169, v169, v165, v160
	ds_read_b64_tr_b16 v[178:179], v162
	ds_read_b64_tr_b16 v[180:181], v169
	v_add_u32_e32 v162, s0, v170
	v_readlane_b32 s0, v255, 10
	v_add3_u32 v162, v162, v166, v160
	v_mfma_f32_32x32x16_bf16 v[16:31], v[244:247], v[236:239], v[16:31]
	v_add_u32_e32 v169, s0, v170
	v_add3_u32 v169, v169, v165, v160
	v_readlane_b32 s0, v255, 11
	v_cvt_pk_bf16_f32 v235, v174, v176
	s_waitcnt lgkmcnt(0)
	v_mfma_f32_32x32x16_bf16 v[0:15], v[240:243], v[236:239], v[0:15]
	ds_read_b64_tr_b16 v[236:237], v162
	ds_read_b64_tr_b16 v[238:239], v169
	v_add_u32_e32 v162, s0, v170
	v_readlane_b32 s0, v255, 12
	v_add3_u32 v162, v162, v166, v160
	s_nop 0
	v_add_u32_e32 v169, s0, v170
	v_readlane_b32 s0, v255, 13
	v_mfma_f32_32x32x16_bf16 v[112:127], v[178:181], v[232:235], v[112:127]
	v_add3_u32 v169, v169, v165, v160
	ds_read_b64_tr_b16 v[176:177], v162
	ds_read_b64_tr_b16 v[178:179], v169
	v_add_u32_e32 v162, s0, v170
	v_readlane_b32 s0, v255, 14
	v_add3_u32 v162, v162, v166, v160
	s_nop 0
	v_add_u32_e32 v169, s0, v170
	s_waitcnt lgkmcnt(0)
	v_mfma_f32_32x32x16_bf16 v[96:111], v[236:239], v[232:235], v[96:111]
	v_add3_u32 v169, v169, v165, v160
	ds_read_b64_tr_b16 v[236:237], v162
	ds_read_b64_tr_b16 v[238:239], v169
	v_readlane_b32 s0, v255, 15
	s_nop 1
	v_add_u32_e32 v162, s0, v170
	v_readlane_b32 s0, v255, 16
	v_add3_u32 v162, v162, v166, v160
	v_mfma_f32_32x32x16_bf16 v[80:95], v[176:179], v[232:235], v[80:95]
	v_add_u32_e32 v169, s0, v170
	v_readlane_b32 s0, v255, 17
	v_add3_u32 v169, v169, v165, v160
	ds_read_b64_tr_b16 v[176:177], v162
	ds_read_b64_tr_b16 v[178:179], v169
	v_add_u32_e32 v162, s0, v170
	v_readlane_b32 s0, v255, 18
	v_add3_u32 v162, v162, v166, v160
	s_waitcnt lgkmcnt(0)
	v_mfma_f32_32x32x16_bf16 v[64:79], v[236:239], v[232:235], v[64:79]
	v_add_u32_e32 v169, s0, v170
	v_add3_u32 v169, v169, v165, v160
	ds_read_b64_tr_b16 v[236:237], v162
	ds_read_b64_tr_b16 v[238:239], v169
	v_readlane_b32 s0, v255, 19
	s_nop 1
	v_add_u32_e32 v162, s0, v170
	v_readlane_b32 s0, v255, 20
	v_add3_u32 v162, v162, v166, v160
	v_mfma_f32_32x32x16_bf16 v[48:63], v[176:179], v[232:235], v[48:63]
	v_add_u32_e32 v169, s0, v170
	v_readlane_b32 s0, v255, 21
	v_add3_u32 v169, v169, v165, v160
	ds_read_b64_tr_b16 v[176:177], v162
	ds_read_b64_tr_b16 v[178:179], v169
	v_add_u32_e32 v162, s0, v170
	v_readlane_b32 s0, v255, 22
	v_add3_u32 v162, v162, v166, v160
	s_waitcnt lgkmcnt(0)
	v_mfma_f32_32x32x16_bf16 v[32:47], v[236:239], v[232:235], v[32:47]
	v_add_u32_e32 v169, s0, v170
	v_add3_u32 v169, v169, v165, v160
	ds_read_b64_tr_b16 v[236:237], v162
	ds_read_b64_tr_b16 v[238:239], v169
	v_mfma_f32_32x32x16_bf16 v[16:31], v[176:179], v[232:235], v[16:31]
	s_waitcnt lgkmcnt(0)
	v_mfma_f32_32x32x16_bf16 v[0:15], v[236:239], v[232:235], v[0:15]
	s_waitcnt vmcnt(0)
	s_waitcnt vmcnt(0)
	s_barrier
; #define MFMA32(a, b, c) __builtin_amdgcn_mfma_f32_32x32x16_bf16((a), (b), (c), 0, 0, 0)
; DI void xattn_unit(const bf16_t* __restrict__ Qg, const bf16_t* __restrict__ Kg, const bf16_t* __restrict__ Vg, bf16_t* __restrict__ Og, lds_t* shm) {
;     ...
; #pragma unroll
;   for (int t = 0; t < 4; ++t) {
;     if (t == 1) { __builtin_amdgcn_sched_barrier(0); asm volatile("s_waitcnt vmcnt(0)" ::: "memory"); __syncthreads(); __builtin_amdgcn_sched_barrier(0); }
;     const unsigned vbase = (t == 0) ? 131072u : (unsigned)t * 32768u;
; #pragma unroll
;     for (int ks = 0; ks < 4; ++ks)
; #pragma unroll
;       for (int c = 0; c < NC; ++c) {
;         const unsigned vo = vbase + (c >> 2) * 16384 + 512 * (c & 3) + 4096 * ks;
;         const bf16x8 vf = tr_pair(shm + vo + va0, shm + vo + 2048 + va1);
;         O[c] = MFMA32(vf, P[t][ks >> 1][ks & 1], O[c]);
;       }
;   }
	v_add_u32_e32 v162, 0, v170
	v_add3_u32 v169, v162, v166, v160
	v_add3_u32 v162, v162, v165, v160
	ds_read_b64_tr_b16 v[232:233], v169 offset:32768
	ds_read_b64_tr_b16 v[234:235], v162 offset:34816
	s_add_i32 s0, 0, 0x10000
	s_add_i32 s2, s2, 1
	v_readlane_b32 s68, v254, 0
	s_nop 1
	ds_read_b64_tr_b16 v[236:237], v169 offset:33280
	ds_read_b64_tr_b16 v[238:239], v162 offset:35328
	ds_read_b64_tr_b16 v[240:241], v169 offset:33792
	ds_read_b64_tr_b16 v[242:243], v162 offset:35840
	s_waitcnt lgkmcnt(4)
	v_mfma_f32_32x32x16_bf16 v[112:127], v[232:235], v[128:131], v[112:127]
	ds_read_b64_tr_b16 v[232:233], v169 offset:34304
	ds_read_b64_tr_b16 v[234:235], v162 offset:36352
	s_waitcnt lgkmcnt(4)
	v_mfma_f32_32x32x16_bf16 v[96:111], v[236:239], v[128:131], v[96:111]
	ds_read_b64_tr_b16 v[236:237], v169 offset:49152
	ds_read_b64_tr_b16 v[238:239], v162 offset:51200
	s_waitcnt lgkmcnt(4)
	v_mfma_f32_32x32x16_bf16 v[80:95], v[240:243], v[128:131], v[80:95]
	ds_read_b64_tr_b16 v[240:241], v169 offset:49664
	ds_read_b64_tr_b16 v[242:243], v162 offset:51712
	s_waitcnt lgkmcnt(4)
	v_mfma_f32_32x32x16_bf16 v[64:79], v[232:235], v[128:131], v[64:79]
	ds_read_b64_tr_b16 v[232:233], v169 offset:50176
	ds_read_b64_tr_b16 v[234:235], v162 offset:52224
	s_waitcnt lgkmcnt(4)
	v_mfma_f32_32x32x16_bf16 v[48:63], v[236:239], v[128:131], v[48:63]
	ds_read_b64_tr_b16 v[236:237], v169 offset:50688
	ds_read_b64_tr_b16 v[238:239], v162 offset:52736
	s_waitcnt lgkmcnt(4)
	v_mfma_f32_32x32x16_bf16 v[32:47], v[240:243], v[128:131], v[32:47]
	ds_read_b64_tr_b16 v[240:241], v169 offset:36864
	ds_read_b64_tr_b16 v[242:243], v162 offset:38912
	s_waitcnt lgkmcnt(4)
	v_mfma_f32_32x32x16_bf16 v[16:31], v[232:235], v[128:131], v[16:31]
	ds_read_b64_tr_b16 v[232:233], v169 offset:37376
	ds_read_b64_tr_b16 v[234:235], v162 offset:39424
	s_waitcnt lgkmcnt(4)
	v_mfma_f32_32x32x16_bf16 v[0:15], v[236:239], v[128:131], v[0:15]
	ds_read_b64_tr_b16 v[236:237], v169 offset:37888
	ds_read_b64_tr_b16 v[238:239], v162 offset:39936
	s_waitcnt lgkmcnt(4)
	v_mfma_f32_32x32x16_bf16 v[112:127], v[240:243], v[132:135], v[112:127]
	ds_read_b64_tr_b16 v[240:241], v169 offset:38400
	ds_read_b64_tr_b16 v[242:243], v162 offset:40448
	s_waitcnt lgkmcnt(4)
	v_mfma_f32_32x32x16_bf16 v[96:111], v[232:235], v[132:135], v[96:111]
	ds_read_b64_tr_b16 v[232:233], v169 offset:53248
	ds_read_b64_tr_b16 v[234:235], v162 offset:55296
	s_waitcnt lgkmcnt(4)
	v_mfma_f32_32x32x16_bf16 v[80:95], v[236:239], v[132:135], v[80:95]
	ds_read_b64_tr_b16 v[236:237], v169 offset:53760
	ds_read_b64_tr_b16 v[238:239], v162 offset:55808
	s_waitcnt lgkmcnt(4)
	v_mfma_f32_32x32x16_bf16 v[64:79], v[240:243], v[132:135], v[64:79]
	ds_read_b64_tr_b16 v[240:241], v169 offset:54272
	ds_read_b64_tr_b16 v[242:243], v162 offset:56320
	s_waitcnt lgkmcnt(4)
	v_mfma_f32_32x32x16_bf16 v[48:63], v[232:235], v[132:135], v[48:63]
	ds_read_b64_tr_b16 v[232:233], v169 offset:54784
	ds_read_b64_tr_b16 v[234:235], v162 offset:56832
	s_waitcnt lgkmcnt(4)
	v_mfma_f32_32x32x16_bf16 v[32:47], v[236:239], v[132:135], v[32:47]
	ds_read_b64_tr_b16 v[236:237], v169 offset:40960
	ds_read_b64_tr_b16 v[238:239], v162 offset:43008
	s_waitcnt lgkmcnt(4)
	v_mfma_f32_32x32x16_bf16 v[16:31], v[240:243], v[132:135], v[16:31]
	ds_read_b64_tr_b16 v[240:241], v169 offset:41472
	ds_read_b64_tr_b16 v[242:243], v162 offset:43520
	s_waitcnt lgkmcnt(4)
	v_mfma_f32_32x32x16_bf16 v[0:15], v[232:235], v[132:135], v[0:15]
	ds_read_b64_tr_b16 v[232:233], v169 offset:41984
	ds_read_b64_tr_b16 v[234:235], v162 offset:44032
	v_cvt_pk_bf16_f32 v132, v203, v204
	v_cvt_pk_bf16_f32 v133, v205, v206
	v_cvt_pk_bf16_f32 v134, v207, v209
	v_cvt_pk_bf16_f32 v135, v211, v219
	s_waitcnt lgkmcnt(4)
	v_mfma_f32_32x32x16_bf16 v[112:127], v[236:239], v[136:139], v[112:127]
	ds_read_b64_tr_b16 v[236:237], v169 offset:42496
	ds_read_b64_tr_b16 v[238:239], v162 offset:44544
	s_waitcnt lgkmcnt(4)
	v_mfma_f32_32x32x16_bf16 v[96:111], v[240:243], v[136:139], v[96:111]
	ds_read_b64_tr_b16 v[240:241], v169 offset:57344
	ds_read_b64_tr_b16 v[242:243], v162 offset:59392
	s_waitcnt lgkmcnt(4)
	v_mfma_f32_32x32x16_bf16 v[80:95], v[232:235], v[136:139], v[80:95]
	ds_read_b64_tr_b16 v[232:233], v169 offset:57856
	ds_read_b64_tr_b16 v[234:235], v162 offset:59904
	s_waitcnt lgkmcnt(4)
	v_mfma_f32_32x32x16_bf16 v[64:79], v[236:239], v[136:139], v[64:79]
	ds_read_b64_tr_b16 v[236:237], v169 offset:58368
	ds_read_b64_tr_b16 v[238:239], v162 offset:60416
	s_waitcnt lgkmcnt(4)
	v_mfma_f32_32x32x16_bf16 v[48:63], v[240:243], v[136:139], v[48:63]
	ds_read_b64_tr_b16 v[240:241], v169 offset:58880
	ds_read_b64_tr_b16 v[242:243], v162 offset:60928
	s_waitcnt lgkmcnt(4)
	v_mfma_f32_32x32x16_bf16 v[32:47], v[232:235], v[136:139], v[32:47]
	ds_read_b64_tr_b16 v[232:233], v169 offset:45056
	ds_read_b64_tr_b16 v[234:235], v162 offset:47104
	s_waitcnt lgkmcnt(4)
	v_mfma_f32_32x32x16_bf16 v[16:31], v[236:239], v[136:139], v[16:31]
	ds_read_b64_tr_b16 v[236:237], v169 offset:45568
	ds_read_b64_tr_b16 v[238:239], v162 offset:47616
	s_waitcnt lgkmcnt(4)
	v_mfma_f32_32x32x16_bf16 v[0:15], v[240:243], v[136:139], v[0:15]
	ds_read_b64_tr_b16 v[240:241], v169 offset:46080
	ds_read_b64_tr_b16 v[242:243], v162 offset:48128
	v_cvt_pk_bf16_f32 v136, v187, v188
	v_cvt_pk_bf16_f32 v137, v189, v190
	v_cvt_pk_bf16_f32 v138, v192, v196
	v_cvt_pk_bf16_f32 v139, v200, v202
	s_waitcnt lgkmcnt(4)
	v_mfma_f32_32x32x16_bf16 v[112:127], v[232:235], v[156:159], v[112:127]
	ds_read_b64_tr_b16 v[232:233], v169 offset:46592
	ds_read_b64_tr_b16 v[234:235], v162 offset:48640
	s_waitcnt lgkmcnt(4)
; #define MFMA32(a, b, c) __builtin_amdgcn_mfma_f32_32x32x16_bf16((a), (b), (c), 0, 0, 0)
; DI void xattn_unit(const bf16_t* __restrict__ Qg, const bf16_t* __restrict__ Kg, const bf16_t* __restrict__ Vg, bf16_t* __restrict__ Og, lds_t* shm) {
;     ...
; #pragma unroll
;   for (int t = 0; t < 4; ++t) {
;     if (t == 1) { __builtin_amdgcn_sched_barrier(0); asm volatile("s_waitcnt vmcnt(0)" ::: "memory"); __syncthreads(); __builtin_amdgcn_sched_barrier(0); }
;     const unsigned vbase = (t == 0) ? 131072u : (unsigned)t * 32768u;
; #pragma unroll
;     for (int ks = 0; ks < 4; ++ks)
; #pragma unroll
;       for (int c = 0; c < NC; ++c) {
;         const unsigned vo = vbase + (c >> 2) * 16384 + 512 * (c & 3) + 4096 * ks;
;         const bf16x8 vf = tr_pair(shm + vo + va0, shm + vo + 2048 + va1);
;         O[c] = MFMA32(vf, P[t][ks >> 1][ks & 1], O[c]);
;       }
;   }
	v_mfma_f32_32x32x16_bf16 v[96:111], v[236:239], v[156:159], v[96:111]
	ds_read_b64_tr_b16 v[236:237], v169 offset:61440
	ds_read_b64_tr_b16 v[238:239], v162 offset:63488
	s_waitcnt lgkmcnt(4)
	v_mfma_f32_32x32x16_bf16 v[80:95], v[240:243], v[156:159], v[80:95]
	ds_read_b64_tr_b16 v[240:241], v169 offset:61952
	ds_read_b64_tr_b16 v[242:243], v162 offset:64000
	s_waitcnt lgkmcnt(4)
	v_mfma_f32_32x32x16_bf16 v[64:79], v[232:235], v[156:159], v[64:79]
	ds_read_b64_tr_b16 v[232:233], v169 offset:62464
	ds_read_b64_tr_b16 v[234:235], v162 offset:64512
	s_waitcnt lgkmcnt(4)
	v_mfma_f32_32x32x16_bf16 v[48:63], v[236:239], v[156:159], v[48:63]
	ds_read_b64_tr_b16 v[236:237], v169 offset:62976
	ds_read_b64_tr_b16 v[238:239], v162 offset:65024
	s_waitcnt lgkmcnt(4)
	v_mfma_f32_32x32x16_bf16 v[32:47], v[240:243], v[156:159], v[32:47]
	v_add_u32_e32 v240, s0, v170
	v_readlane_b32 s0, v255, 23
	s_nop 1
	v_add3_u32 v240, v240, v166, v160
	s_nop 0
	v_add_u32_e32 v241, s0, v170
	v_add3_u32 v242, v241, v165, v160
	ds_read_b64_tr_b16 v[240:241], v240
	ds_read_b64_tr_b16 v[242:243], v242
	s_add_i32 s0, 0, 0x10200
	s_waitcnt lgkmcnt(4)
	v_mfma_f32_32x32x16_bf16 v[16:31], v[232:235], v[156:159], v[16:31]
	v_add_u32_e32 v232, s0, v170
	v_readlane_b32 s0, v255, 24
	s_nop 1
	v_add3_u32 v232, v232, v166, v160
	s_nop 0
	v_add_u32_e32 v233, s0, v170
	v_add3_u32 v234, v233, v165, v160
	ds_read_b64_tr_b16 v[232:233], v232
	ds_read_b64_tr_b16 v[234:235], v234
	s_add_i32 s0, 0, 0x10400
	s_waitcnt lgkmcnt(4)
	v_mfma_f32_32x32x16_bf16 v[0:15], v[236:239], v[156:159], v[0:15]
	v_add_u32_e32 v236, s0, v170
	v_readlane_b32 s0, v255, 25
	s_nop 1
	v_add3_u32 v236, v236, v166, v160
	s_nop 0
	v_add_u32_e32 v237, s0, v170
	v_add3_u32 v238, v237, v165, v160
	ds_read_b64_tr_b16 v[236:237], v236
	ds_read_b64_tr_b16 v[238:239], v238
	s_add_i32 s0, 0, 0x10600
	s_waitcnt lgkmcnt(4)
	v_mfma_f32_32x32x16_bf16 v[112:127], v[240:243], v[152:155], v[112:127]
	v_add_u32_e32 v240, s0, v170
	v_readlane_b32 s0, v255, 26
	s_nop 1
	v_add3_u32 v240, v240, v166, v160
	s_nop 0
	v_add_u32_e32 v241, s0, v170
	v_add3_u32 v242, v241, v165, v160
	ds_read_b64_tr_b16 v[240:241], v240
	ds_read_b64_tr_b16 v[242:243], v242
	s_add_i32 s0, 0, 0x14000
	s_waitcnt lgkmcnt(4)
	v_mfma_f32_32x32x16_bf16 v[96:111], v[232:235], v[152:155], v[96:111]
	v_add_u32_e32 v232, s0, v170
	v_readlane_b32 s0, v255, 27
	s_nop 1
	v_add3_u32 v232, v232, v166, v160
	s_nop 0
	v_add_u32_e32 v233, s0, v170
	v_add3_u32 v234, v233, v165, v160
	ds_read_b64_tr_b16 v[232:233], v232
	ds_read_b64_tr_b16 v[234:235], v234
	s_add_i32 s0, 0, 0x14200
	s_waitcnt lgkmcnt(4)
	v_mfma_f32_32x32x16_bf16 v[80:95], v[236:239], v[152:155], v[80:95]
	v_add_u32_e32 v236, s0, v170
	v_readlane_b32 s0, v255, 28
	s_nop 1
	v_add3_u32 v236, v236, v166, v160
	s_nop 0
	v_add_u32_e32 v237, s0, v170
	v_add3_u32 v238, v237, v165, v160
	ds_read_b64_tr_b16 v[236:237], v236
	ds_read_b64_tr_b16 v[238:239], v238
	s_add_i32 s0, 0, 0x14400
	s_waitcnt lgkmcnt(4)
	v_mfma_f32_32x32x16_bf16 v[64:79], v[240:243], v[152:155], v[64:79]
	v_add_u32_e32 v240, s0, v170
	v_readlane_b32 s0, v255, 29
	s_nop 1
	v_add3_u32 v240, v240, v166, v160
	s_nop 0
	v_add_u32_e32 v241, s0, v170
	v_add3_u32 v242, v241, v165, v160
	ds_read_b64_tr_b16 v[240:241], v240
	ds_read_b64_tr_b16 v[242:243], v242
	s_add_i32 s0, 0, 0x14600
	s_waitcnt lgkmcnt(4)
	v_mfma_f32_32x32x16_bf16 v[48:63], v[232:235], v[152:155], v[48:63]
	v_add_u32_e32 v232, s0, v170
	v_readlane_b32 s0, v255, 30
	s_nop 1
	v_add3_u32 v232, v232, v166, v160
	s_nop 0
	v_add_u32_e32 v233, s0, v170
	v_add3_u32 v234, v233, v165, v160
	ds_read_b64_tr_b16 v[232:233], v232
	ds_read_b64_tr_b16 v[234:235], v234
	v_readlane_b32 s0, v255, 31
	s_nop 1
	s_waitcnt lgkmcnt(4)
	v_mfma_f32_32x32x16_bf16 v[32:47], v[236:239], v[152:155], v[32:47]
	v_add_u32_e32 v236, s0, v170
	v_readlane_b32 s0, v255, 32
	s_nop 1
	v_add3_u32 v236, v236, v166, v160
	s_nop 0
	v_add_u32_e32 v237, s0, v170
	v_add3_u32 v238, v237, v165, v160
	ds_read_b64_tr_b16 v[236:237], v236
	ds_read_b64_tr_b16 v[238:239], v238
	v_readlane_b32 s0, v255, 33
	s_nop 1
	s_waitcnt lgkmcnt(4)
	v_mfma_f32_32x32x16_bf16 v[16:31], v[240:243], v[152:155], v[16:31]
	v_add_u32_e32 v240, s0, v170
	v_readlane_b32 s0, v255, 34
	s_nop 1
	v_add3_u32 v240, v240, v166, v160
	s_nop 0
	v_add_u32_e32 v241, s0, v170
	v_add3_u32 v242, v241, v165, v160
	ds_read_b64_tr_b16 v[240:241], v240
	ds_read_b64_tr_b16 v[242:243], v242
	v_readlane_b32 s0, v255, 35
	s_nop 1
	s_waitcnt lgkmcnt(4)
	v_mfma_f32_32x32x16_bf16 v[0:15], v[232:235], v[152:155], v[0:15]
	v_add_u32_e32 v232, s0, v170
	v_readlane_b32 s0, v255, 36
	s_nop 1
	v_add3_u32 v232, v232, v166, v160
	s_nop 0
	v_add_u32_e32 v233, s0, v170
	v_add3_u32 v234, v233, v165, v160
	ds_read_b64_tr_b16 v[232:233], v232
	ds_read_b64_tr_b16 v[234:235], v234
	v_readlane_b32 s0, v255, 37
	s_nop 1
	s_waitcnt lgkmcnt(4)
	v_mfma_f32_32x32x16_bf16 v[112:127], v[236:239], v[148:151], v[112:127]
	v_add_u32_e32 v236, s0, v170
	v_readlane_b32 s0, v255, 38
	s_nop 1
	v_add3_u32 v236, v236, v166, v160
	s_nop 0
	v_add_u32_e32 v237, s0, v170
	v_add3_u32 v238, v237, v165, v160
	ds_read_b64_tr_b16 v[236:237], v236
	ds_read_b64_tr_b16 v[238:239], v238
	v_readlane_b32 s0, v255, 39
	s_nop 1
	s_waitcnt lgkmcnt(4)
	v_mfma_f32_32x32x16_bf16 v[96:111], v[240:243], v[148:151], v[96:111]
	v_add_u32_e32 v240, s0, v170
	v_readlane_b32 s0, v255, 40
	s_nop 1
	v_add3_u32 v240, v240, v166, v160
	s_nop 0
	v_add_u32_e32 v241, s0, v170
	v_add3_u32 v242, v241, v165, v160
	ds_read_b64_tr_b16 v[240:241], v240
	ds_read_b64_tr_b16 v[242:243], v242
	v_readlane_b32 s0, v255, 41
	s_nop 1
	s_waitcnt lgkmcnt(4)
; #define MFMA32(a, b, c) __builtin_amdgcn_mfma_f32_32x32x16_bf16((a), (b), (c), 0, 0, 0)
; DI void xattn_unit(const bf16_t* __restrict__ Qg, const bf16_t* __restrict__ Kg, const bf16_t* __restrict__ Vg, bf16_t* __restrict__ Og, lds_t* shm) {
;     ...
; #pragma unroll
;   for (int t = 0; t < 4; ++t) {
;     if (t == 1) { __builtin_amdgcn_sched_barrier(0); asm volatile("s_waitcnt vmcnt(0)" ::: "memory"); __syncthreads(); __builtin_amdgcn_sched_barrier(0); }
;     const unsigned vbase = (t == 0) ? 131072u : (unsigned)t * 32768u;
; #pragma unroll
;     for (int ks = 0; ks < 4; ++ks)
; #pragma unroll
;       for (int c = 0; c < NC; ++c) {
;         const unsigned vo = vbase + (c >> 2) * 16384 + 512 * (c & 3) + 4096 * ks;
;         const bf16x8 vf = tr_pair(shm + vo + va0, shm + vo + 2048 + va1);
;         O[c] = MFMA32(vf, P[t][ks >> 1][ks & 1], O[c]);
;       }
;   }
	v_mfma_f32_32x32x16_bf16 v[80:95], v[232:235], v[148:151], v[80:95]
	v_add_u32_e32 v232, s0, v170
	v_readlane_b32 s0, v255, 42
	s_nop 1
	v_add3_u32 v232, v232, v166, v160
	s_nop 0
	v_add_u32_e32 v233, s0, v170
	v_add3_u32 v234, v233, v165, v160
	ds_read_b64_tr_b16 v[232:233], v232
	ds_read_b64_tr_b16 v[234:235], v234
	v_readlane_b32 s0, v255, 43
	s_nop 1
	s_waitcnt lgkmcnt(4)
	v_mfma_f32_32x32x16_bf16 v[64:79], v[236:239], v[148:151], v[64:79]
	v_add_u32_e32 v236, s0, v170
	v_readlane_b32 s0, v255, 44
	s_nop 1
	v_add3_u32 v236, v236, v166, v160
	s_nop 0
	v_add_u32_e32 v237, s0, v170
	v_add3_u32 v238, v237, v165, v160
	ds_read_b64_tr_b16 v[236:237], v236
	ds_read_b64_tr_b16 v[238:239], v238
	v_readlane_b32 s0, v255, 45
	s_nop 1
	s_waitcnt lgkmcnt(4)
	v_mfma_f32_32x32x16_bf16 v[48:63], v[240:243], v[148:151], v[48:63]
	v_add_u32_e32 v240, s0, v170
	v_readlane_b32 s0, v255, 46
	s_nop 1
	v_add3_u32 v240, v240, v166, v160
	s_nop 0
	v_add_u32_e32 v241, s0, v170
	v_add3_u32 v242, v241, v165, v160
	ds_read_b64_tr_b16 v[240:241], v240
	ds_read_b64_tr_b16 v[242:243], v242
	s_add_i32 s0, 0, 0x12000
	s_waitcnt lgkmcnt(4)
	v_mfma_f32_32x32x16_bf16 v[32:47], v[232:235], v[148:151], v[32:47]
	v_add_u32_e32 v232, s0, v170
	v_readlane_b32 s0, v255, 47
	s_nop 1
	v_add3_u32 v232, v232, v166, v160
	s_nop 0
	v_add_u32_e32 v233, s0, v170
	v_add3_u32 v234, v233, v165, v160
	ds_read_b64_tr_b16 v[232:233], v232
	ds_read_b64_tr_b16 v[234:235], v234
	s_add_i32 s0, 0, 0x12200
	s_waitcnt lgkmcnt(4)
	v_mfma_f32_32x32x16_bf16 v[16:31], v[236:239], v[148:151], v[16:31]
	v_add_u32_e32 v236, s0, v170
	v_readlane_b32 s0, v255, 48
	s_nop 1
	v_add3_u32 v236, v236, v166, v160
	s_nop 0
	v_add_u32_e32 v237, s0, v170
	v_add3_u32 v238, v237, v165, v160
	ds_read_b64_tr_b16 v[236:237], v236
	ds_read_b64_tr_b16 v[238:239], v238
	s_add_i32 s0, 0, 0x12400
	s_waitcnt lgkmcnt(4)
	v_mfma_f32_32x32x16_bf16 v[0:15], v[240:243], v[148:151], v[0:15]
	v_add_u32_e32 v240, s0, v170
	v_readlane_b32 s0, v255, 49
	s_nop 1
	v_add3_u32 v240, v240, v166, v160
	s_nop 0
	v_add_u32_e32 v241, s0, v170
	v_add3_u32 v242, v241, v165, v160
	ds_read_b64_tr_b16 v[240:241], v240
	ds_read_b64_tr_b16 v[242:243], v242
	s_add_i32 s0, 0, 0x12600
	s_waitcnt lgkmcnt(4)
	v_mfma_f32_32x32x16_bf16 v[112:127], v[232:235], v[140:143], v[112:127]
	v_add_u32_e32 v232, s0, v170
	v_readlane_b32 s0, v255, 50
	s_nop 1
	v_add3_u32 v232, v232, v166, v160
	s_nop 0
	v_add_u32_e32 v233, s0, v170
	v_add3_u32 v234, v233, v165, v160
	ds_read_b64_tr_b16 v[232:233], v232
	ds_read_b64_tr_b16 v[234:235], v234
	s_add_i32 s0, 0, 0x16000
	s_waitcnt lgkmcnt(4)
	v_mfma_f32_32x32x16_bf16 v[96:111], v[236:239], v[140:143], v[96:111]
	v_add_u32_e32 v236, s0, v170
	v_readlane_b32 s0, v255, 51
	s_nop 1
	v_add3_u32 v236, v236, v166, v160
	s_nop 0
	v_add_u32_e32 v237, s0, v170
	v_add3_u32 v238, v237, v165, v160
	ds_read_b64_tr_b16 v[236:237], v236
	ds_read_b64_tr_b16 v[238:239], v238
	s_add_i32 s0, 0, 0x16200
	s_waitcnt lgkmcnt(4)
	v_mfma_f32_32x32x16_bf16 v[80:95], v[240:243], v[140:143], v[80:95]
	v_add_u32_e32 v240, s0, v170
	v_readlane_b32 s0, v255, 52
	s_nop 1
	v_add3_u32 v240, v240, v166, v160
	s_nop 0
	v_add_u32_e32 v241, s0, v170
	v_add3_u32 v242, v241, v165, v160
	ds_read_b64_tr_b16 v[240:241], v240
	ds_read_b64_tr_b16 v[242:243], v242
	s_add_i32 s0, 0, 0x16400
	s_waitcnt lgkmcnt(4)
	v_mfma_f32_32x32x16_bf16 v[64:79], v[232:235], v[140:143], v[64:79]
	v_add_u32_e32 v232, s0, v170
	v_readlane_b32 s0, v255, 53
	s_nop 1
	v_add3_u32 v232, v232, v166, v160
	s_nop 0
	v_add_u32_e32 v233, s0, v170
	v_add3_u32 v234, v233, v165, v160
	ds_read_b64_tr_b16 v[232:233], v232
	ds_read_b64_tr_b16 v[234:235], v234
	s_add_i32 s0, 0, 0x16600
	s_waitcnt lgkmcnt(4)
	v_mfma_f32_32x32x16_bf16 v[48:63], v[236:239], v[140:143], v[48:63]
	v_add_u32_e32 v236, s0, v170
	v_readlane_b32 s0, v255, 54
	s_nop 1
	v_add3_u32 v236, v236, v166, v160
	s_nop 0
	v_add_u32_e32 v237, s0, v170
	v_add3_u32 v238, v237, v165, v160
	ds_read_b64_tr_b16 v[236:237], v236
	ds_read_b64_tr_b16 v[238:239], v238
	v_readlane_b32 s0, v255, 55
	s_nop 1
	s_waitcnt lgkmcnt(4)
	v_mfma_f32_32x32x16_bf16 v[32:47], v[240:243], v[140:143], v[32:47]
	v_add_u32_e32 v240, s0, v170
	v_readlane_b32 s0, v255, 56
	s_nop 1
	v_add3_u32 v240, v240, v166, v160
	v_add_u32_e32 v241, s0, v170
	v_add3_u32 v242, v241, v165, v160
	ds_read_b64_tr_b16 v[240:241], v240
	ds_read_b64_tr_b16 v[242:243], v242
	v_readlane_b32 s0, v255, 57
	s_nop 1
	s_waitcnt lgkmcnt(4)
	v_mfma_f32_32x32x16_bf16 v[16:31], v[232:235], v[140:143], v[16:31]
	v_add_u32_e32 v232, s0, v170
	v_readlane_b32 s0, v255, 58
	s_nop 1
	v_add3_u32 v232, v232, v166, v160
	v_add_u32_e32 v233, s0, v170
	v_add3_u32 v234, v233, v165, v160
	ds_read_b64_tr_b16 v[232:233], v232
	ds_read_b64_tr_b16 v[234:235], v234
	v_readlane_b32 s0, v255, 59
	s_nop 1
	s_waitcnt lgkmcnt(4)
	v_mfma_f32_32x32x16_bf16 v[0:15], v[236:239], v[140:143], v[0:15]
	v_add_u32_e32 v236, s0, v170
	v_readlane_b32 s0, v255, 60
	s_nop 1
	v_add3_u32 v236, v236, v166, v160
	v_add_u32_e32 v237, s0, v170
	v_add3_u32 v238, v237, v165, v160
	ds_read_b64_tr_b16 v[236:237], v236
	ds_read_b64_tr_b16 v[238:239], v238
	v_readlane_b32 s0, v255, 61
	s_nop 1
	v_cvt_pk_bf16_f32 v140, v171, v172
	s_waitcnt lgkmcnt(4)
	v_mfma_f32_32x32x16_bf16 v[112:127], v[240:243], v[144:147], v[112:127]
	v_add_u32_e32 v240, s0, v170
	v_readlane_b32 s0, v255, 62
	s_nop 1
	v_add3_u32 v240, v240, v166, v160
	v_add_u32_e32 v241, s0, v170
	v_add3_u32 v242, v241, v165, v160
	ds_read_b64_tr_b16 v[240:241], v240
	ds_read_b64_tr_b16 v[242:243], v242
	v_cvt_pk_bf16_f32 v141, v173, v175
	s_waitcnt lgkmcnt(4)
; #define MFMA32(a, b, c) __builtin_amdgcn_mfma_f32_32x32x16_bf16((a), (b), (c), 0, 0, 0)
; DI void xattn_unit(const bf16_t* __restrict__ Qg, const bf16_t* __restrict__ Kg, const bf16_t* __restrict__ Vg, bf16_t* __restrict__ Og, lds_t* shm) {
;     ...
; #pragma unroll
;   for (int t = 0; t < 4; ++t) {
;     if (t == 1) { __builtin_amdgcn_sched_barrier(0); asm volatile("s_waitcnt vmcnt(0)" ::: "memory"); __syncthreads(); __builtin_amdgcn_sched_barrier(0); }
;     const unsigned vbase = (t == 0) ? 131072u : (unsigned)t * 32768u;
; #pragma unroll
;     for (int ks = 0; ks < 4; ++ks)
; #pragma unroll
;       for (int c = 0; c < NC; ++c) {
;         const unsigned vo = vbase + (c >> 2) * 16384 + 512 * (c & 3) + 4096 * ks;
;         const bf16x8 vf = tr_pair(shm + vo + va0, shm + vo + 2048 + va1);
;         O[c] = MFMA32(vf, P[t][ks >> 1][ks & 1], O[c]);
;       }
;   }
	v_mfma_f32_32x32x16_bf16 v[96:111], v[232:235], v[144:147], v[96:111]
	v_add_u32_e32 v232, s83, v170
	v_add_u32_e32 v233, s84, v170
	v_add3_u32 v232, v232, v166, v160
	v_add3_u32 v234, v233, v165, v160
	ds_read_b64_tr_b16 v[232:233], v232
	ds_read_b64_tr_b16 v[234:235], v234
	s_add_i32 s0, 0, 0x18000
	v_cvt_pk_bf16_f32 v142, v182, v184
	s_waitcnt lgkmcnt(4)
	v_mfma_f32_32x32x16_bf16 v[80:95], v[236:239], v[144:147], v[80:95]
	v_add_u32_e32 v236, s85, v170
	v_add_u32_e32 v237, s86, v170
	v_add3_u32 v236, v236, v166, v160
	v_add3_u32 v238, v237, v165, v160
	ds_read_b64_tr_b16 v[236:237], v236
	ds_read_b64_tr_b16 v[238:239], v238
	v_cvt_pk_bf16_f32 v143, v185, v186
	s_waitcnt lgkmcnt(4)
	v_mfma_f32_32x32x16_bf16 v[64:79], v[240:243], v[144:147], v[64:79]
	v_add_u32_e32 v240, s87, v170
	v_add_u32_e32 v241, s88, v170
	v_add3_u32 v240, v240, v166, v160
	v_add3_u32 v242, v241, v165, v160
	ds_read_b64_tr_b16 v[240:241], v240
	ds_read_b64_tr_b16 v[242:243], v242
	s_waitcnt lgkmcnt(4)
	v_mfma_f32_32x32x16_bf16 v[48:63], v[232:235], v[144:147], v[48:63]
	v_add_u32_e32 v232, s89, v170
	v_add_u32_e32 v233, s90, v170
	v_add3_u32 v232, v232, v166, v160
	v_add3_u32 v234, v233, v165, v160
	ds_read_b64_tr_b16 v[232:233], v232
	ds_read_b64_tr_b16 v[234:235], v234
	s_waitcnt lgkmcnt(4)
	v_mfma_f32_32x32x16_bf16 v[32:47], v[236:239], v[144:147], v[32:47]
	v_add_u32_e32 v236, s0, v170
	v_add_u32_e32 v237, s91, v170
	v_add3_u32 v236, v236, v166, v160
	v_add3_u32 v238, v237, v165, v160
	ds_read_b64_tr_b16 v[236:237], v236
	ds_read_b64_tr_b16 v[238:239], v238
	s_add_i32 s0, 0, 0x18200
	s_waitcnt lgkmcnt(4)
	v_mfma_f32_32x32x16_bf16 v[16:31], v[240:243], v[144:147], v[16:31]
	v_add_u32_e32 v240, s0, v170
	v_add_u32_e32 v241, s92, v170
	v_add3_u32 v240, v240, v166, v160
	v_add3_u32 v242, v241, v165, v160
	ds_read_b64_tr_b16 v[240:241], v240
	ds_read_b64_tr_b16 v[242:243], v242
	s_add_i32 s0, 0, 0x18400
	s_waitcnt lgkmcnt(4)
	v_mfma_f32_32x32x16_bf16 v[0:15], v[232:235], v[144:147], v[0:15]
	v_add_u32_e32 v232, s0, v170
	v_add_u32_e32 v233, s93, v170
	v_add3_u32 v232, v232, v166, v160
	v_add3_u32 v234, v233, v165, v160
	ds_read_b64_tr_b16 v[232:233], v232
	ds_read_b64_tr_b16 v[234:235], v234
	s_add_i32 s0, 0, 0x18600
	v_cvt_pk_bf16_f32 v128, v222, v223
	s_waitcnt lgkmcnt(4)
	v_mfma_f32_32x32x16_bf16 v[112:127], v[236:239], v[140:143], v[112:127]
	v_add_u32_e32 v236, s0, v170
	v_add_u32_e32 v237, s94, v170
	v_add3_u32 v236, v236, v166, v160
	v_add3_u32 v238, v237, v165, v160
	ds_read_b64_tr_b16 v[236:237], v236
	ds_read_b64_tr_b16 v[238:239], v238
	s_add_i32 s0, 0, 0x1c000
	v_cvt_pk_bf16_f32 v129, v224, v225
	s_waitcnt lgkmcnt(4)
	v_mfma_f32_32x32x16_bf16 v[96:111], v[240:243], v[140:143], v[96:111]
	v_add_u32_e32 v240, s0, v170
	v_add_u32_e32 v241, s95, v170
	v_add3_u32 v240, v240, v166, v160
	v_add3_u32 v242, v241, v165, v160
	ds_read_b64_tr_b16 v[240:241], v240
	ds_read_b64_tr_b16 v[242:243], v242
	s_add_i32 s0, 0, 0x1c200
	v_cvt_pk_bf16_f32 v130, v226, v228
	s_waitcnt lgkmcnt(4)
	v_mfma_f32_32x32x16_bf16 v[80:95], v[232:235], v[140:143], v[80:95]
	v_add_u32_e32 v232, s0, v170
	v_add_u32_e32 v233, s96, v170
	v_add3_u32 v232, v232, v166, v160
	v_add3_u32 v234, v233, v165, v160
	ds_read_b64_tr_b16 v[232:233], v232
	ds_read_b64_tr_b16 v[234:235], v234
	s_add_i32 s0, 0, 0x1c400
	v_cvt_pk_bf16_f32 v131, v229, v230
	s_waitcnt lgkmcnt(4)
	v_mfma_f32_32x32x16_bf16 v[64:79], v[236:239], v[140:143], v[64:79]
	v_add_u32_e32 v236, s0, v170
	v_add_u32_e32 v237, s97, v170
	v_add3_u32 v236, v236, v166, v160
	v_add3_u32 v238, v237, v165, v160
	ds_read_b64_tr_b16 v[236:237], v236
	ds_read_b64_tr_b16 v[238:239], v238
	s_add_i32 s0, 0, 0x1c600
	s_waitcnt lgkmcnt(4)
	v_mfma_f32_32x32x16_bf16 v[48:63], v[240:243], v[140:143], v[48:63]
	v_add_u32_e32 v240, s0, v170
	v_add_u32_e32 v241, s8, v170
	v_add3_u32 v240, v240, v166, v160
	v_add3_u32 v242, v241, v165, v160
	ds_read_b64_tr_b16 v[240:241], v240
	ds_read_b64_tr_b16 v[242:243], v242
	s_add_i32 s0, 0, 0x1a000
	s_waitcnt lgkmcnt(4)
	v_mfma_f32_32x32x16_bf16 v[32:47], v[232:235], v[140:143], v[32:47]
	v_add_u32_e32 v232, s9, v170
	v_add_u32_e32 v233, s10, v170
	v_add3_u32 v232, v232, v166, v160
	v_add3_u32 v234, v233, v165, v160
	ds_read_b64_tr_b16 v[232:233], v232
	ds_read_b64_tr_b16 v[234:235], v234
	s_waitcnt lgkmcnt(4)
	v_mfma_f32_32x32x16_bf16 v[16:31], v[236:239], v[140:143], v[16:31]
	v_add_u32_e32 v236, s11, v170
	v_add_u32_e32 v237, s18, v170
	v_add3_u32 v236, v236, v166, v160
	v_add3_u32 v238, v237, v165, v160
	ds_read_b64_tr_b16 v[236:237], v236
	ds_read_b64_tr_b16 v[238:239], v238
	s_waitcnt lgkmcnt(4)
	v_mfma_f32_32x32x16_bf16 v[0:15], v[240:243], v[140:143], v[0:15]
	v_add_u32_e32 v240, s19, v170
	v_add_u32_e32 v241, s34, v170
	v_add3_u32 v240, v240, v166, v160
	v_add3_u32 v242, v241, v165, v160
	ds_read_b64_tr_b16 v[240:241], v240
	ds_read_b64_tr_b16 v[242:243], v242
	s_waitcnt lgkmcnt(4)
	v_mfma_f32_32x32x16_bf16 v[112:127], v[232:235], v[136:139], v[112:127]
	v_add_u32_e32 v232, s20, v170
	v_add_u32_e32 v233, s21, v170
	v_add3_u32 v232, v232, v166, v160
	v_add3_u32 v234, v233, v165, v160
	ds_read_b64_tr_b16 v[232:233], v232
	ds_read_b64_tr_b16 v[234:235], v234
	s_waitcnt lgkmcnt(4)
	v_mfma_f32_32x32x16_bf16 v[96:111], v[236:239], v[136:139], v[96:111]
	v_add_u32_e32 v236, s22, v170
	v_add_u32_e32 v237, s23, v170
	v_add3_u32 v236, v236, v166, v160
	v_add3_u32 v238, v237, v165, v160
	ds_read_b64_tr_b16 v[236:237], v236
	ds_read_b64_tr_b16 v[238:239], v238
	s_waitcnt lgkmcnt(4)
; #define MFMA32(a, b, c) __builtin_amdgcn_mfma_f32_32x32x16_bf16((a), (b), (c), 0, 0, 0)
; DI void xattn_unit(const bf16_t* __restrict__ Qg, const bf16_t* __restrict__ Kg, const bf16_t* __restrict__ Vg, bf16_t* __restrict__ Og, lds_t* shm) {
;     ...
; #pragma unroll
;   for (int t = 0; t < 4; ++t) {
;     if (t == 1) { __builtin_amdgcn_sched_barrier(0); asm volatile("s_waitcnt vmcnt(0)" ::: "memory"); __syncthreads(); __builtin_amdgcn_sched_barrier(0); }
;     const unsigned vbase = (t == 0) ? 131072u : (unsigned)t * 32768u;
; #pragma unroll
;     for (int ks = 0; ks < 4; ++ks)
; #pragma unroll
;       for (int c = 0; c < NC; ++c) {
;         const unsigned vo = vbase + (c >> 2) * 16384 + 512 * (c & 3) + 4096 * ks;
;         const bf16x8 vf = tr_pair(shm + vo + va0, shm + vo + 2048 + va1);
;         O[c] = MFMA32(vf, P[t][ks >> 1][ks & 1], O[c]);
;       }
;   }
	v_mfma_f32_32x32x16_bf16 v[80:95], v[240:243], v[136:139], v[80:95]
	v_add_u32_e32 v240, s3, v170
	v_add_u32_e32 v241, s15, v170
	v_add3_u32 v240, v240, v166, v160
	v_add3_u32 v242, v241, v165, v160
	ds_read_b64_tr_b16 v[240:241], v240
	ds_read_b64_tr_b16 v[242:243], v242
	s_waitcnt lgkmcnt(4)
	v_mfma_f32_32x32x16_bf16 v[64:79], v[232:235], v[136:139], v[64:79]
	v_add_u32_e32 v232, s35, v170
	v_add_u32_e32 v233, s40, v170
	v_add3_u32 v232, v232, v166, v160
	v_add3_u32 v234, v233, v165, v160
	ds_read_b64_tr_b16 v[232:233], v232
	ds_read_b64_tr_b16 v[234:235], v234
	s_waitcnt lgkmcnt(4)
	v_mfma_f32_32x32x16_bf16 v[48:63], v[236:239], v[136:139], v[48:63]
	v_add_u32_e32 v236, s41, v170
	v_add_u32_e32 v237, s42, v170
	v_add3_u32 v236, v236, v166, v160
	v_add3_u32 v238, v237, v165, v160
	ds_read_b64_tr_b16 v[236:237], v236
	ds_read_b64_tr_b16 v[238:239], v238
	s_waitcnt lgkmcnt(4)
	v_mfma_f32_32x32x16_bf16 v[32:47], v[240:243], v[136:139], v[32:47]
	v_add_u32_e32 v240, s0, v170
	v_add_u32_e32 v241, s43, v170
	v_add3_u32 v240, v240, v166, v160
	v_add3_u32 v242, v241, v165, v160
	ds_read_b64_tr_b16 v[240:241], v240
	ds_read_b64_tr_b16 v[242:243], v242
	s_add_i32 s0, 0, 0x1a200
	s_waitcnt lgkmcnt(4)
	v_mfma_f32_32x32x16_bf16 v[16:31], v[232:235], v[136:139], v[16:31]
	v_add_u32_e32 v232, s0, v170
	v_add_u32_e32 v233, s46, v170
	v_add3_u32 v232, v232, v166, v160
	v_add3_u32 v234, v233, v165, v160
	ds_read_b64_tr_b16 v[232:233], v232
	ds_read_b64_tr_b16 v[234:235], v234
	s_add_i32 s0, 0, 0x1a400
	s_waitcnt lgkmcnt(4)
	v_mfma_f32_32x32x16_bf16 v[0:15], v[236:239], v[136:139], v[0:15]
	v_add_u32_e32 v236, s0, v170
	v_add_u32_e32 v237, s47, v170
	v_add3_u32 v236, v236, v166, v160
	v_add3_u32 v238, v237, v165, v160
	ds_read_b64_tr_b16 v[236:237], v236
	ds_read_b64_tr_b16 v[238:239], v238
	s_add_i32 s0, 0, 0x1a600
	s_waitcnt lgkmcnt(4)
	v_mfma_f32_32x32x16_bf16 v[112:127], v[240:243], v[132:135], v[112:127]
	v_add_u32_e32 v240, s0, v170
	v_add_u32_e32 v241, s48, v170
	v_add3_u32 v240, v240, v166, v160
	v_add3_u32 v242, v241, v165, v160
	ds_read_b64_tr_b16 v[240:241], v240
	ds_read_b64_tr_b16 v[242:243], v242
	s_add_i32 s0, 0, 0x1e000
	s_waitcnt lgkmcnt(4)
	v_mfma_f32_32x32x16_bf16 v[96:111], v[232:235], v[132:135], v[96:111]
	v_add_u32_e32 v232, s0, v170
	v_add_u32_e32 v233, s49, v170
	v_add3_u32 v232, v232, v166, v160
	v_add3_u32 v234, v233, v165, v160
	ds_read_b64_tr_b16 v[232:233], v232
	ds_read_b64_tr_b16 v[234:235], v234
	s_add_i32 s0, 0, 0x1e200
	s_waitcnt lgkmcnt(4)
	v_mfma_f32_32x32x16_bf16 v[80:95], v[236:239], v[132:135], v[80:95]
	v_add_u32_e32 v236, s0, v170
	v_add_u32_e32 v237, s52, v170
	v_add3_u32 v236, v236, v166, v160
	v_add3_u32 v238, v237, v165, v160
	ds_read_b64_tr_b16 v[236:237], v236
	ds_read_b64_tr_b16 v[238:239], v238
	s_add_i32 s0, 0, 0x1e400
	s_waitcnt lgkmcnt(4)
	v_mfma_f32_32x32x16_bf16 v[64:79], v[240:243], v[132:135], v[64:79]
	v_add_u32_e32 v240, s0, v170
	v_add_u32_e32 v241, s53, v170
	v_add3_u32 v240, v240, v166, v160
	v_add3_u32 v242, v241, v165, v160
	ds_read_b64_tr_b16 v[240:241], v240
	ds_read_b64_tr_b16 v[242:243], v242
	s_add_i32 s0, 0, 0x1e600
	s_waitcnt lgkmcnt(4)
	v_mfma_f32_32x32x16_bf16 v[48:63], v[232:235], v[132:135], v[48:63]
	v_add_u32_e32 v232, s0, v170
	v_add_u32_e32 v233, s54, v170
	v_add3_u32 v232, v232, v166, v160
	v_add3_u32 v234, v233, v165, v160
	ds_read_b64_tr_b16 v[232:233], v232
	ds_read_b64_tr_b16 v[234:235], v234
	s_waitcnt lgkmcnt(4)
	v_mfma_f32_32x32x16_bf16 v[32:47], v[236:239], v[132:135], v[32:47]
	v_add_u32_e32 v236, s55, v170
	v_add_u32_e32 v237, s56, v170
	v_add3_u32 v236, v236, v166, v160
	v_add3_u32 v238, v237, v165, v160
	ds_read_b64_tr_b16 v[236:237], v236
	ds_read_b64_tr_b16 v[238:239], v238
	s_waitcnt lgkmcnt(4)
	v_mfma_f32_32x32x16_bf16 v[16:31], v[240:243], v[132:135], v[16:31]
	v_add_u32_e32 v240, s57, v170
	v_add_u32_e32 v241, s58, v170
	v_add3_u32 v240, v240, v166, v160
	v_add3_u32 v242, v241, v165, v160
	ds_read_b64_tr_b16 v[240:241], v240
	ds_read_b64_tr_b16 v[242:243], v242
	s_waitcnt lgkmcnt(4)
	v_mfma_f32_32x32x16_bf16 v[0:15], v[232:235], v[132:135], v[0:15]
	v_add_u32_e32 v232, s59, v170
	v_add_u32_e32 v233, s60, v170
	v_add3_u32 v232, v232, v166, v160
	v_add3_u32 v234, v233, v165, v160
	ds_read_b64_tr_b16 v[232:233], v232
	ds_read_b64_tr_b16 v[234:235], v234
	s_waitcnt lgkmcnt(4)
	v_mfma_f32_32x32x16_bf16 v[112:127], v[236:239], v[128:131], v[112:127]
	v_add_u32_e32 v236, s61, v170
	v_add_u32_e32 v237, s62, v170
	v_add3_u32 v236, v236, v166, v160
	v_add3_u32 v238, v237, v165, v160
	ds_read_b64_tr_b16 v[236:237], v236
	ds_read_b64_tr_b16 v[238:239], v238
	s_waitcnt lgkmcnt(4)
	v_mfma_f32_32x32x16_bf16 v[96:111], v[240:243], v[128:131], v[96:111]
	v_add_u32_e32 v240, s63, v170
	v_add_u32_e32 v241, s64, v170
	v_add3_u32 v240, v240, v166, v160
	v_add3_u32 v242, v241, v165, v160
	ds_read_b64_tr_b16 v[240:241], v240
	ds_read_b64_tr_b16 v[242:243], v242
	s_waitcnt lgkmcnt(4)
	v_mfma_f32_32x32x16_bf16 v[80:95], v[232:235], v[128:131], v[80:95]
	v_add_u32_e32 v232, s65, v170
	v_add_u32_e32 v233, s6, v170
	v_add3_u32 v232, v232, v166, v160
	v_add3_u32 v234, v233, v165, v160
	ds_read_b64_tr_b16 v[232:233], v232
	ds_read_b64_tr_b16 v[234:235], v234
	s_waitcnt lgkmcnt(4)
	v_mfma_f32_32x32x16_bf16 v[64:79], v[236:239], v[128:131], v[64:79]
	v_add_u32_e32 v236, s7, v170
	v_add_u32_e32 v237, s66, v170
	v_add3_u32 v236, v236, v166, v160
	v_add3_u32 v238, v237, v165, v160
	ds_read_b64_tr_b16 v[236:237], v236
	ds_read_b64_tr_b16 v[238:239], v238
	s_waitcnt lgkmcnt(4)
; DI unsigned pk2(float lo, float hi) { bf2_t v = __builtin_convertvector((f32x2){lo, hi}, bf2_t); return __builtin_bit_cast(unsigned, v); }
; #define MFMA32(a, b, c) __builtin_amdgcn_mfma_f32_32x32x16_bf16((a), (b), (c), 0, 0, 0)
; DI void xattn_unit(const bf16_t* __restrict__ Qg, const bf16_t* __restrict__ Kg, const bf16_t* __restrict__ Vg, bf16_t* __restrict__ Og, lds_t* shm) {
;     ...
; #pragma unroll
;   for (int t = 0; t < 4; ++t) {
;     if (t == 1) { __builtin_amdgcn_sched_barrier(0); asm volatile("s_waitcnt vmcnt(0)" ::: "memory"); __syncthreads(); __builtin_amdgcn_sched_barrier(0); }
;     const unsigned vbase = (t == 0) ? 131072u : (unsigned)t * 32768u;
; #pragma unroll
;     for (int ks = 0; ks < 4; ++ks)
; #pragma unroll
;       for (int c = 0; c < NC; ++c) {
;         const unsigned vo = vbase + (c >> 2) * 16384 + 512 * (c & 3) + 4096 * ks;
;         const bf16x8 vf = tr_pair(shm + vo + va0, shm + vo + 2048 + va1);
;         O[c] = MFMA32(vf, P[t][ks >> 1][ks & 1], O[c]);
;       }
;   }
;   const float inv = 1.0f / l;
;   const unsigned ooff = ((unsigned)l31 * (unsigned)LDQ + 4u * h) * 2u;
; #pragma unroll
;   for (int c = 0; c < NC; ++c)
; #pragma unroll
;     for (int g4 = 0; g4 < 4; ++g4) {
;       u32x2 w; w.x = pk2(O[c][4 * g4 + 0] * inv, O[c][4 * g4 + 1] * inv); w.y = pk2(O[c][4 * g4 + 2] * inv, O[c][4 * g4 + 3] * inv);
;       gst<u32x2>(Og + 32 * c + 8 * g4, ooff, w);
;     }
	v_mfma_f32_32x32x16_bf16 v[48:63], v[240:243], v[128:131], v[48:63]
	v_add_u32_e32 v240, s16, v170
	v_add_u32_e32 v241, s17, v170
	v_add3_u32 v240, v240, v166, v160
	v_add3_u32 v242, v241, v165, v160
	ds_read_b64_tr_b16 v[240:241], v240
	ds_read_b64_tr_b16 v[242:243], v242
	s_waitcnt lgkmcnt(4)
	v_mfma_f32_32x32x16_bf16 v[32:47], v[232:235], v[128:131], v[32:47]
	s_waitcnt lgkmcnt(2)
	v_mfma_f32_32x32x16_bf16 v[16:31], v[236:239], v[128:131], v[16:31]
	s_waitcnt lgkmcnt(0)
	v_mfma_f32_32x32x16_bf16 v[0:15], v[240:243], v[128:131], v[0:15]
	v_add_f32_e32 v128, v167, v168
	v_div_scale_f32 v129, s[0:1], v128, v128, 1.0
	v_rcp_f32_e32 v130, v129
	v_readlane_b32 s0, v254, 6
	s_mov_b32 s28, s0
	s_mul_i32 s0, s2, s0
	v_fma_f32 v131, -v129, v130, 1.0
	v_fmac_f32_e32 v130, v131, v130
	v_div_scale_f32 v131, vcc, 1.0, v128, 1.0
	v_mul_f32_e32 v132, v131, v130
	v_fma_f32 v133, -v129, v132, v131
	v_fmac_f32_e32 v132, v133, v130
	v_fma_f32 v129, -v129, v132, v131
	v_div_fmas_f32 v129, v129, v130, v132
	v_div_fixup_f32 v128, v129, v128, 1.0
	v_lshl_or_b32 v129, v163, 3, v164
	v_pk_mul_f32 v[112:113], v[128:129], v[112:113] op_sel_hi:[0,1]
	v_pk_mul_f32 v[114:115], v[128:129], v[114:115] op_sel_hi:[0,1]
	v_pk_mul_f32 v[96:97], v[128:129], v[96:97] op_sel_hi:[0,1]
	v_pk_mul_f32 v[98:99], v[128:129], v[98:99] op_sel_hi:[0,1]
	v_pk_mul_f32 v[80:81], v[128:129], v[80:81] op_sel_hi:[0,1]
	v_pk_mul_f32 v[82:83], v[128:129], v[82:83] op_sel_hi:[0,1]
	v_pk_mul_f32 v[64:65], v[128:129], v[64:65] op_sel_hi:[0,1]
	v_pk_mul_f32 v[66:67], v[128:129], v[66:67] op_sel_hi:[0,1]
	v_pk_mul_f32 v[48:49], v[128:129], v[48:49] op_sel_hi:[0,1]
	v_pk_mul_f32 v[50:51], v[128:129], v[50:51] op_sel_hi:[0,1]
	v_pk_mul_f32 v[32:33], v[128:129], v[32:33] op_sel_hi:[0,1]
	v_pk_mul_f32 v[34:35], v[128:129], v[34:35] op_sel_hi:[0,1]
	v_pk_mul_f32 v[16:17], v[128:129], v[16:17] op_sel_hi:[0,1]
	v_pk_mul_f32 v[18:19], v[128:129], v[18:19] op_sel_hi:[0,1]
	v_pk_mul_f32 v[0:1], v[128:129], v[0:1] op_sel_hi:[0,1]
	v_pk_mul_f32 v[2:3], v[128:129], v[2:3] op_sel_hi:[0,1]
	v_cvt_pk_bf16_f32 v112, v112, v113
	v_cvt_pk_bf16_f32 v113, v114, v115
	v_cvt_pk_bf16_f32 v96, v96, v97
	v_cvt_pk_bf16_f32 v97, v98, v99
	v_cvt_pk_bf16_f32 v80, v80, v81
	v_cvt_pk_bf16_f32 v81, v82, v83
	v_cvt_pk_bf16_f32 v64, v64, v65
	v_cvt_pk_bf16_f32 v65, v66, v67
	v_cvt_pk_bf16_f32 v48, v48, v49
	v_cvt_pk_bf16_f32 v49, v50, v51
	v_cvt_pk_bf16_f32 v32, v32, v33
	v_cvt_pk_bf16_f32 v33, v34, v35
	v_cvt_pk_bf16_f32 v16, v16, v17
	v_cvt_pk_bf16_f32 v17, v18, v19
	v_cvt_pk_bf16_f32 v0, v0, v1
	v_cvt_pk_bf16_f32 v1, v2, v3
	global_store_dwordx2 v129, v[112:113], s[30:31]
	v_pk_mul_f32 v[112:113], v[128:129], v[116:117] op_sel_hi:[0,1]
	v_pk_mul_f32 v[114:115], v[128:129], v[118:119] op_sel_hi:[0,1]
	global_store_dwordx2 v129, v[96:97], s[30:31] offset:64
	v_pk_mul_f32 v[96:97], v[128:129], v[100:101] op_sel_hi:[0,1]
	v_pk_mul_f32 v[98:99], v[128:129], v[102:103] op_sel_hi:[0,1]
	global_store_dwordx2 v129, v[80:81], s[30:31] offset:128
	v_pk_mul_f32 v[80:81], v[128:129], v[84:85] op_sel_hi:[0,1]
	v_pk_mul_f32 v[82:83], v[128:129], v[86:87] op_sel_hi:[0,1]
	global_store_dwordx2 v129, v[64:65], s[30:31] offset:192
	v_pk_mul_f32 v[64:65], v[128:129], v[68:69] op_sel_hi:[0,1]
	v_pk_mul_f32 v[66:67], v[128:129], v[70:71] op_sel_hi:[0,1]
	global_store_dwordx2 v129, v[48:49], s[30:31] offset:256
	v_pk_mul_f32 v[48:49], v[128:129], v[52:53] op_sel_hi:[0,1]
	v_pk_mul_f32 v[50:51], v[128:129], v[54:55] op_sel_hi:[0,1]
	global_store_dwordx2 v129, v[32:33], s[30:31] offset:320
	v_pk_mul_f32 v[32:33], v[128:129], v[36:37] op_sel_hi:[0,1]
	v_pk_mul_f32 v[34:35], v[128:129], v[38:39] op_sel_hi:[0,1]
	global_store_dwordx2 v129, v[16:17], s[30:31] offset:384
	v_pk_mul_f32 v[16:17], v[128:129], v[20:21] op_sel_hi:[0,1]
	v_pk_mul_f32 v[18:19], v[128:129], v[22:23] op_sel_hi:[0,1]
	global_store_dwordx2 v129, v[0:1], s[30:31] offset:448
	v_pk_mul_f32 v[0:1], v[128:129], v[4:5] op_sel_hi:[0,1]
	v_pk_mul_f32 v[2:3], v[128:129], v[6:7] op_sel_hi:[0,1]
	v_cvt_pk_bf16_f32 v112, v112, v113
	v_cvt_pk_bf16_f32 v113, v114, v115
	v_cvt_pk_bf16_f32 v96, v96, v97
	v_cvt_pk_bf16_f32 v97, v98, v99
	v_cvt_pk_bf16_f32 v80, v80, v81
	v_cvt_pk_bf16_f32 v81, v82, v83
	v_cvt_pk_bf16_f32 v64, v64, v65
	v_cvt_pk_bf16_f32 v65, v66, v67
	v_cvt_pk_bf16_f32 v48, v48, v49
	v_cvt_pk_bf16_f32 v49, v50, v51
	v_cvt_pk_bf16_f32 v32, v32, v33
	v_cvt_pk_bf16_f32 v33, v34, v35
	v_cvt_pk_bf16_f32 v16, v16, v17
	v_cvt_pk_bf16_f32 v17, v18, v19
	v_cvt_pk_bf16_f32 v0, v0, v1
	v_cvt_pk_bf16_f32 v1, v2, v3
; DI unsigned pk2(float lo, float hi) { bf2_t v = __builtin_convertvector((f32x2){lo, hi}, bf2_t); return __builtin_bit_cast(unsigned, v); }
; DI void xattn_unit(const bf16_t* __restrict__ Qg, const bf16_t* __restrict__ Kg, const bf16_t* __restrict__ Vg, bf16_t* __restrict__ Og, lds_t* shm) {
;     ...
;   const unsigned ooff = ((unsigned)l31 * (unsigned)LDQ + 4u * h) * 2u;
; #pragma unroll
;   for (int c = 0; c < NC; ++c)
; #pragma unroll
;     for (int g4 = 0; g4 < 4; ++g4) {
;       u32x2 w; w.x = pk2(O[c][4 * g4 + 0] * inv, O[c][4 * g4 + 1] * inv); w.y = pk2(O[c][4 * g4 + 2] * inv, O[c][4 * g4 + 3] * inv);
;       gst<u32x2>(Og + 32 * c + 8 * g4, ooff, w);
;     }
	global_store_dwordx2 v129, v[112:113], s[30:31] offset:16
	v_pk_mul_f32 v[112:113], v[128:129], v[120:121] op_sel_hi:[0,1]
	v_pk_mul_f32 v[114:115], v[128:129], v[122:123] op_sel_hi:[0,1]
	global_store_dwordx2 v129, v[96:97], s[30:31] offset:80
	v_pk_mul_f32 v[96:97], v[128:129], v[104:105] op_sel_hi:[0,1]
	v_pk_mul_f32 v[98:99], v[128:129], v[106:107] op_sel_hi:[0,1]
	global_store_dwordx2 v129, v[80:81], s[30:31] offset:144
	v_pk_mul_f32 v[80:81], v[128:129], v[88:89] op_sel_hi:[0,1]
	v_pk_mul_f32 v[82:83], v[128:129], v[90:91] op_sel_hi:[0,1]
	global_store_dwordx2 v129, v[64:65], s[30:31] offset:208
	v_pk_mul_f32 v[64:65], v[128:129], v[72:73] op_sel_hi:[0,1]
	v_pk_mul_f32 v[66:67], v[128:129], v[74:75] op_sel_hi:[0,1]
	global_store_dwordx2 v129, v[48:49], s[30:31] offset:272
	v_pk_mul_f32 v[48:49], v[128:129], v[56:57] op_sel_hi:[0,1]
	v_pk_mul_f32 v[50:51], v[128:129], v[58:59] op_sel_hi:[0,1]
	global_store_dwordx2 v129, v[32:33], s[30:31] offset:336
	v_pk_mul_f32 v[32:33], v[128:129], v[40:41] op_sel_hi:[0,1]
	v_pk_mul_f32 v[34:35], v[128:129], v[42:43] op_sel_hi:[0,1]
	global_store_dwordx2 v129, v[16:17], s[30:31] offset:400
	v_pk_mul_f32 v[16:17], v[128:129], v[24:25] op_sel_hi:[0,1]
	v_pk_mul_f32 v[18:19], v[128:129], v[26:27] op_sel_hi:[0,1]
	global_store_dwordx2 v129, v[0:1], s[30:31] offset:464
	v_pk_mul_f32 v[0:1], v[128:129], v[8:9] op_sel_hi:[0,1]
	v_pk_mul_f32 v[2:3], v[128:129], v[10:11] op_sel_hi:[0,1]
	v_cvt_pk_bf16_f32 v112, v112, v113
	v_cvt_pk_bf16_f32 v113, v114, v115
	v_cvt_pk_bf16_f32 v96, v96, v97
	v_cvt_pk_bf16_f32 v97, v98, v99
	v_cvt_pk_bf16_f32 v80, v80, v81
	v_cvt_pk_bf16_f32 v81, v82, v83
	v_cvt_pk_bf16_f32 v64, v64, v65
	v_cvt_pk_bf16_f32 v65, v66, v67
	v_cvt_pk_bf16_f32 v48, v48, v49
	v_cvt_pk_bf16_f32 v49, v50, v51
	v_cvt_pk_bf16_f32 v32, v32, v33
	v_cvt_pk_bf16_f32 v33, v34, v35
	v_cvt_pk_bf16_f32 v16, v16, v17
	v_cvt_pk_bf16_f32 v17, v18, v19
	v_cvt_pk_bf16_f32 v0, v0, v1
	v_cvt_pk_bf16_f32 v1, v2, v3
	global_store_dwordx2 v129, v[112:113], s[30:31] offset:32
	v_pk_mul_f32 v[112:113], v[128:129], v[124:125] op_sel_hi:[0,1]
	v_pk_mul_f32 v[114:115], v[128:129], v[126:127] op_sel_hi:[0,1]
	global_store_dwordx2 v129, v[96:97], s[30:31] offset:96
	v_pk_mul_f32 v[96:97], v[128:129], v[108:109] op_sel_hi:[0,1]
	v_pk_mul_f32 v[98:99], v[128:129], v[110:111] op_sel_hi:[0,1]
	global_store_dwordx2 v129, v[80:81], s[30:31] offset:160
	v_pk_mul_f32 v[80:81], v[128:129], v[92:93] op_sel_hi:[0,1]
	v_pk_mul_f32 v[82:83], v[128:129], v[94:95] op_sel_hi:[0,1]
	global_store_dwordx2 v129, v[64:65], s[30:31] offset:224
	v_pk_mul_f32 v[64:65], v[128:129], v[76:77] op_sel_hi:[0,1]
	v_pk_mul_f32 v[66:67], v[128:129], v[78:79] op_sel_hi:[0,1]
	global_store_dwordx2 v129, v[48:49], s[30:31] offset:288
	v_pk_mul_f32 v[48:49], v[128:129], v[60:61] op_sel_hi:[0,1]
	v_pk_mul_f32 v[50:51], v[128:129], v[62:63] op_sel_hi:[0,1]
	global_store_dwordx2 v129, v[32:33], s[30:31] offset:352
	v_pk_mul_f32 v[32:33], v[128:129], v[44:45] op_sel_hi:[0,1]
	v_pk_mul_f32 v[34:35], v[128:129], v[46:47] op_sel_hi:[0,1]
	global_store_dwordx2 v129, v[16:17], s[30:31] offset:416
	v_pk_mul_f32 v[16:17], v[128:129], v[28:29] op_sel_hi:[0,1]
	v_pk_mul_f32 v[18:19], v[128:129], v[30:31] op_sel_hi:[0,1]
	global_store_dwordx2 v129, v[0:1], s[30:31] offset:480
	v_pk_mul_f32 v[0:1], v[128:129], v[12:13] op_sel_hi:[0,1]
	v_pk_mul_f32 v[2:3], v[128:129], v[14:15] op_sel_hi:[0,1]
	s_add_i32 s0, s0, s68
	s_add_i32 s33, s33, s28
	v_cvt_pk_bf16_f32 v112, v112, v113
	v_cvt_pk_bf16_f32 v113, v114, v115
	v_cvt_pk_bf16_f32 v96, v96, v97
	v_cvt_pk_bf16_f32 v97, v98, v99
	v_cvt_pk_bf16_f32 v80, v80, v81
	v_cvt_pk_bf16_f32 v81, v82, v83
	v_cvt_pk_bf16_f32 v64, v64, v65
	v_cvt_pk_bf16_f32 v65, v66, v67
	v_cvt_pk_bf16_f32 v48, v48, v49
	v_cvt_pk_bf16_f32 v49, v50, v51
	v_cvt_pk_bf16_f32 v32, v32, v33
	v_cvt_pk_bf16_f32 v33, v34, v35
	v_cvt_pk_bf16_f32 v16, v16, v17
	v_cvt_pk_bf16_f32 v17, v18, v19
	v_cvt_pk_bf16_f32 v0, v0, v1
	v_cvt_pk_bf16_f32 v1, v2, v3
	s_cmpk_lt_i32 s33, 0x200
	global_store_dwordx2 v129, v[112:113], s[30:31] offset:48
	global_store_dwordx2 v129, v[96:97], s[30:31] offset:112
	global_store_dwordx2 v129, v[80:81], s[30:31] offset:176
	global_store_dwordx2 v129, v[64:65], s[30:31] offset:240
	global_store_dwordx2 v129, v[48:49], s[30:31] offset:304
	global_store_dwordx2 v129, v[32:33], s[30:31] offset:368
	global_store_dwordx2 v129, v[16:17], s[30:31] offset:432
	global_store_dwordx2 v129, v[0:1], s[30:31] offset:496
	v_readlane_b32 s1, v254, 7
	s_cbranch_scc0 .LBB0_634
